# all 15 gemm_phase prologues: second batch of stage loads issued before the first wait (vmcnt(4)->vmcnt(10) moved after them)
# baseline (speedup 1.0000x reference)
.LBB0_184:
	s_add_u32 s28, s12, 0x4e00000
	s_addc_u32 s29, s13, 0
	s_add_u32 s33, s12, 0x2100000
	s_addc_u32 s35, s13, 0
	s_sext_i32_i8 s20, s8
	s_lshl_b32 s8, s8, 9
	s_and_b32 s8, s8, 0x600
	s_add_u32 s10, s28, s10
	s_addc_u32 s11, s29, s11
	s_add_u32 s60, s10, s8
	s_addc_u32 s61, s11, 0
	s_lshl_b32 s10, s20, 8
	s_ashr_i32 s11, s10, 31
	s_lshl_b64 s[10:11], s[10:11], 2
	s_add_u32 s58, s33, s10
	s_mov_b64 s[38:39], 0x80
	s_addc_u32 s59, s35, s11
	v_lshl_add_u64 v[10:11], v[2:3], 0, s[38:39]
	s_add_i32 m0, s7, 0x18000
	s_mov_b64 s[42:43], 0x20080
	global_load_lds_dwordx4 v[10:11], off
	v_lshl_add_u64 v[10:11], v[2:3], 0, s[42:43]
	s_add_i32 m0, s7, 0x1a000
	s_add_i32 s37, s7, 0x8000
	global_load_lds_dwordx4 v[10:11], off
	v_lshl_add_u64 v[10:11], v[4:5], 0, s[38:39]
	s_mov_b32 m0, s37
	s_add_i32 s40, s7, 0xa000
	global_load_lds_dwordx4 v[10:11], off
	v_lshl_add_u64 v[4:5], v[4:5], 0, s[42:43]
	s_mov_b32 m0, s40
	s_mov_b64 s[44:45], 0x40080
	global_load_lds_dwordx4 v[4:5], off
	v_lshl_add_u64 v[4:5], v[2:3], 0, s[44:45]
	s_add_i32 m0, s7, 0x1c000
	s_mov_b64 s[46:47], 0x60080
	global_load_lds_dwordx4 v[4:5], off
	v_lshl_add_u64 v[2:3], v[2:3], 0, s[46:47]
	s_add_i32 m0, s7, 0x1e000
	v_bfe_u32 v153, v6, 4, 2
	global_load_lds_dwordx4 v[2:3], off
	s_waitcnt vmcnt(10)
	s_barrier
	s_lshl_b32 s1, s1, 5
	v_and_b32_e32 v152, 15, v6
	v_lshlrev_b32_e32 v2, 4, v153
	v_lshlrev_b32_e32 v3, 2, v6
	s_and_b32 s70, s1, 0x60
	v_lshl_or_b32 v2, v152, 6, v2
	s_lshl_b32 s8, s9, 13
	v_and_b32_e32 v3, 32, v3
	s_lshl_b32 s1, s70, 7
	v_bitop3_b32 v4, v2, s8, v3 bitop3:0xde
	v_bitop3_b32 v154, v2, s1, v3 bitop3:0xde
	v_lshlrev_b32_e32 v2, 14, v8
	s_lshl_b32 s41, s9, 6
	v_and_b32_e32 v2, 0xffff8000, v2
	s_waitcnt vmcnt(6)
	s_cmpk_lt_u32 s0, 0x100
	v_lshl_add_u32 v2, v7, 11, v2
	v_and_b32_e32 v3, 1, v8
	s_cselect_b64 s[48:49], -1, 0
	v_lshl_or_b32 v2, v3, 6, v2
	s_add_i32 s75, 0, 0x10000
	s_add_i32 s76, 0, 0x14000
	s_mov_b32 s71, 0x18000
	s_mov_b32 s72, 0x8000
	s_ashr_i32 s73, s90, 31
	s_mov_b32 s74, s90
	v_lshl_add_u32 v142, v9, 1, v2
	v_mov_b32_e32 v143, v139
	v_mov_b64_e32 v[144:145], 0x100
	v_mov_b64_e32 v[146:147], 0xff
	v_add_u32_e32 v155, s75, v154
	v_add_u32_e32 v156, 0, v4
	v_add_u32_e32 v157, s76, v154
	s_lshl_b32 s20, s70, 1
	s_mov_b32 s77, 0x40000
	s_mov_b32 s78, 0x48000
	s_mov_b32 s79, 0x50000
	s_mov_b32 s80, s21
	s_barrier
	s_branch .LBB0_187

.LBB0_269:
	s_mov_b64 s[52:53], 0x80
	v_lshl_add_u64 v[8:9], v[2:3], 0, s[52:53]
	s_add_i32 m0, s27, 0x18000
	s_mov_b64 s[54:55], 0x8080
	global_load_lds_dwordx4 v[8:9], off
	v_lshl_add_u64 v[8:9], v[2:3], 0, s[54:55]
	s_add_i32 m0, s27, 0x1a000
	s_add_i32 s35, s27, 0x8000
	global_load_lds_dwordx4 v[8:9], off
	v_lshl_add_u64 v[8:9], v[4:5], 0, s[52:53]
	s_mov_b32 m0, s35
	s_mov_b64 s[56:57], 0x20080
	s_add_i32 s39, s27, 0xa000
	global_load_lds_dwordx4 v[8:9], off
	v_lshl_add_u64 v[4:5], v[4:5], 0, s[56:57]
	s_mov_b32 m0, s39
	s_mov_b64 s[58:59], 0x10080
	global_load_lds_dwordx4 v[4:5], off
	v_lshl_add_u64 v[4:5], v[2:3], 0, s[58:59]
	s_add_i32 m0, s27, 0x1c000
	s_mov_b64 s[60:61], 0x18080
	global_load_lds_dwordx4 v[4:5], off
	v_lshl_add_u64 v[2:3], v[2:3], 0, s[60:61]
	s_add_i32 m0, s27, 0x1e000
	s_lshl_b32 s0, s0, 5
	global_load_lds_dwordx4 v[2:3], off
	s_waitcnt vmcnt(10)
	s_barrier
	v_bfe_u32 v150, v6, 4, 2
	s_and_b32 s41, s0, 0x60
	v_and_b32_e32 v149, 15, v6
	s_lshl_b32 s40, s30, 6
	v_lshlrev_b32_e32 v2, 4, v150
	s_lshl_b32 s30, s30, 13
	v_lshlrev_b32_e32 v3, 2, v6
	s_lshl_b32 s0, s41, 7
	v_lshl_or_b32 v2, v149, 6, v2
	v_and_b32_e32 v3, 32, v3
	s_waitcnt vmcnt(6)
	s_cmpk_lt_u32 s1, 0x100
	v_bitop3_b32 v4, v2, s30, v3 bitop3:0xde
	v_bitop3_b32 v151, v2, s0, v3 bitop3:0xde
	s_cselect_b64 s[62:63], -1, 0
	s_add_i32 s84, s2, s90
	s_add_i32 s87, 0, 0x10000
	s_add_i32 s88, 0, 0x14000
	s_lshl_b32 s85, s84, 17
	s_lshl_b32 s86, s90, 17
	v_add_u32_e32 v152, s87, v151
	v_add_u32_e32 v153, 0, v4
	v_add_u32_e32 v154, s88, v151
	s_mov_b64 s[64:65], 0x100
	s_mov_b64 s[66:67], 0x180
	s_lshl_b32 s50, s41, 1
	s_barrier
	s_branch .LBB0_272

.LBB0_473:
	s_add_u32 s85, s50, 0x2359000
	s_addc_u32 s86, s51, 0
	s_add_u32 s87, s50, 0x2399000
	s_addc_u32 s88, s51, 0
	v_bfe_u32 v156, v6, 4, 2
	s_lshl_b32 s0, s0, 5
	v_and_b32_e32 v139, 15, v6
	v_lshlrev_b32_e32 v7, 4, v156
	v_lshlrev_b32_e32 v6, 2, v6
	s_and_b32 s90, s0, 0x60
	s_lshl_b32 s89, s30, 6
	v_lshl_or_b32 v7, v139, 6, v7
	s_lshl_b32 s30, s30, 13
	v_and_b32_e32 v6, 32, v6
	s_lshl_b32 s0, s90, 7
	s_mov_b64 s[50:51], 0x80
	v_bitop3_b32 v8, v7, s30, v6 bitop3:0xde
	v_bitop3_b32 v157, v7, s0, v6 bitop3:0xde
	v_lshl_add_u64 v[6:7], v[2:3], 0, s[50:51]
	s_add_i32 m0, s29, 0x18000
	s_mov_b64 s[52:53], 0x20080
	global_load_lds_dwordx4 v[6:7], off
	v_lshl_add_u64 v[6:7], v[2:3], 0, s[52:53]
	s_add_i32 m0, s29, 0x1a000
	s_add_i32 s91, s29, 0x8000
	global_load_lds_dwordx4 v[6:7], off
	v_lshl_add_u64 v[6:7], v[4:5], 0, s[50:51]
	s_mov_b32 m0, s91
	s_mov_b64 s[54:55], 0x8080
	s_add_i32 s92, s29, 0xa000
	global_load_lds_dwordx4 v[6:7], off
	v_lshl_add_u64 v[4:5], v[4:5], 0, s[54:55]
	s_mov_b32 m0, s92
	s_mov_b64 s[56:57], 0x40080
	global_load_lds_dwordx4 v[4:5], off
	v_lshl_add_u64 v[4:5], v[2:3], 0, s[56:57]
	s_add_i32 m0, s29, 0x1c000
	s_mov_b64 s[58:59], 0x60080
	global_load_lds_dwordx4 v[4:5], off
	v_lshl_add_u64 v[2:3], v[2:3], 0, s[58:59]
	s_add_i32 m0, s29, 0x1e000
	s_cmpk_lt_u32 s1, 0x100
	global_load_lds_dwordx4 v[2:3], off
	s_waitcnt vmcnt(10)
	s_barrier
	v_readlane_b32 s30, v254, 16
	s_waitcnt vmcnt(6)
	s_cselect_b64 s[60:61], -1, 0
	s_add_i32 s0, s2, s30
	s_sub_i32 s93, s0, 48
	s_lshl_b32 s95, s30, 8
	s_add_i32 s96, 0, 0x10000
	s_add_i32 s97, 0, 0x14000
	s_lshl_b32 s94, s93, 8
	s_addk_i32 s95, 0xe800
	v_add_u32_e32 v158, s96, v157
	v_add_u32_e32 v159, 0, v8
	v_add_u32_e32 v160, s97, v157
	s_mov_b64 s[62:63], 0x100
	s_mov_b64 s[64:65], 0x180
	s_lshl_b32 s48, s90, 1
	s_barrier
	v_readlane_b32 s31, v254, 17
	s_branch .LBB0_476

.LBB0_647:
	v_bfe_u32 v136, v9, 4, 2
	v_and_b32_e32 v137, 15, v9
	v_lshlrev_b32_e32 v10, 4, v136
	v_lshlrev_b32_e32 v9, 2, v9
	s_lshl_b32 s7, s9, 6
	v_lshl_or_b32 v10, v137, 6, v10
	s_lshl_b32 s9, s9, 13
	v_and_b32_e32 v9, 32, v9
	s_lshl_b32 s1, s1, 5
	v_bitop3_b32 v12, v10, s9, v9 bitop3:0xde
	s_and_b32 s9, s1, 0x60
	s_lshl_b32 s1, s9, 7
	s_mov_b64 s[42:43], 0x80
	v_bitop3_b32 v9, v10, s1, v9 bitop3:0xde
	v_lshl_add_u64 v[10:11], v[2:3], 0, s[42:43]
	s_add_i32 m0, s4, 0x18000
	s_mov_b64 s[44:45], 0x20080
	global_load_lds_dwordx4 v[10:11], off
	v_lshl_add_u64 v[10:11], v[2:3], 0, s[44:45]
	s_add_i32 m0, s4, 0x1a000
	s_add_i32 s11, s4, 0x8000
	global_load_lds_dwordx4 v[10:11], off
	v_lshl_add_u64 v[10:11], v[4:5], 0, s[42:43]
	s_mov_b32 m0, s11
	s_add_i32 s24, s4, 0xa000
	global_load_lds_dwordx4 v[10:11], off
	v_lshl_add_u64 v[4:5], v[4:5], 0, s[44:45]
	s_mov_b32 m0, s24
	s_mov_b64 s[46:47], 0x40080
	global_load_lds_dwordx4 v[4:5], off
	v_lshl_add_u64 v[4:5], v[2:3], 0, s[46:47]
	s_add_i32 m0, s4, 0x1c000
	s_mov_b64 s[48:49], 0x60080
	global_load_lds_dwordx4 v[4:5], off
	v_lshl_add_u64 v[2:3], v[2:3], 0, s[48:49]
	s_add_i32 m0, s4, 0x1e000
	s_add_i32 s28, 0, 0x10000
	global_load_lds_dwordx4 v[2:3], off
	s_waitcnt vmcnt(10)
	s_barrier
	v_lshlrev_b32_e32 v2, 14, v6
	v_and_b32_e32 v2, 0xffff8000, v2
	v_lshl_add_u32 v2, v7, 11, v2
	v_and_b32_e32 v3, 1, v6
	s_waitcnt vmcnt(6)
	v_lshl_or_b32 v2, v3, 6, v2
	s_add_i32 s33, 0, 0x14000
	s_add_i32 s38, 0, 0x18000
	s_add_i32 s40, 0, 0x1c000
	v_lshl_add_u32 v2, v8, 1, v2
	v_mov_b32_e32 v3, v133
	v_add_u32_e32 v139, s28, v9
	s_mov_b32 s50, 0xfffe0000
	v_add_u32_e32 v141, s33, v9
	s_add_i32 s28, s28, s0
	s_add_i32 s33, s33, s0
	v_add_u32_e32 v142, s38, v9
	v_add_u32_e32 v143, s40, v9
	s_add_i32 s38, s38, s0
	s_add_i32 s40, s40, s0
	v_lshl_add_u64 v[134:135], s[12:13], 0, v[2:3]
	s_mov_b32 s25, -2
	v_add_u32_e32 v140, 0, v12
	s_mov_b32 s51, -1
	s_add_i32 s26, s4, 0xc000
	s_add_i32 s27, s4, 0xe000
	s_add_i32 s29, s28, 0x2000
	s_add_i32 s35, s33, 0x2000
	s_add_i32 s39, s38, 0x2000
	s_add_i32 s41, s40, 0x2000
	s_mov_b64 s[52:53], 0x60080
	v_mov_b32_e32 v2, v133
	v_mov_b32_e32 v4, v133
	v_mov_b32_e32 v5, v133
	v_mov_b32_e32 v6, v133
	v_mov_b32_e32 v7, v133
	v_mov_b32_e32 v8, v133
	v_mov_b32_e32 v9, v133
	v_mov_b32_e32 v10, v133
	v_mov_b32_e32 v11, v133
	v_mov_b32_e32 v12, v133
	v_mov_b32_e32 v13, v133
	v_mov_b32_e32 v14, v133
	v_mov_b32_e32 v15, v133
	v_mov_b32_e32 v16, v133
	v_mov_b32_e32 v17, v133
	v_mov_b32_e32 v18, v133
	v_mov_b32_e32 v19, v133
	v_mov_b32_e32 v20, v133
	v_mov_b32_e32 v21, v133
	v_mov_b32_e32 v22, v133
	v_mov_b32_e32 v23, v133
	v_mov_b32_e32 v24, v133
	v_mov_b32_e32 v25, v133
	v_mov_b32_e32 v26, v133
	v_mov_b32_e32 v27, v133
	v_mov_b32_e32 v28, v133
	v_mov_b32_e32 v29, v133
	v_mov_b32_e32 v30, v133
	v_mov_b32_e32 v31, v133
	v_mov_b32_e32 v32, v133
	v_mov_b32_e32 v33, v133
	v_mov_b32_e32 v54, v133
	v_mov_b32_e32 v55, v133
	v_mov_b32_e32 v56, v133
	v_mov_b32_e32 v57, v133
	v_mov_b32_e32 v62, v133
	v_mov_b32_e32 v63, v133
	v_mov_b32_e32 v64, v133
	v_mov_b32_e32 v65, v133
	v_mov_b32_e32 v70, v133
	v_mov_b32_e32 v71, v133
	v_mov_b32_e32 v72, v133
	v_mov_b32_e32 v73, v133
	v_mov_b32_e32 v78, v133
	v_mov_b32_e32 v79, v133
	v_mov_b32_e32 v80, v133
	v_mov_b32_e32 v81, v133
	v_mov_b32_e32 v82, v133
	v_mov_b32_e32 v83, v133
	v_mov_b32_e32 v84, v133
	v_mov_b32_e32 v85, v133
	v_mov_b32_e32 v86, v133
	v_mov_b32_e32 v87, v133
	v_mov_b32_e32 v88, v133
	v_mov_b32_e32 v89, v133
	v_mov_b32_e32 v90, v133
	v_mov_b32_e32 v91, v133
	v_mov_b32_e32 v92, v133
	v_mov_b32_e32 v93, v133
	v_mov_b32_e32 v94, v133
	v_mov_b32_e32 v95, v133
	v_mov_b32_e32 v96, v133
	v_mov_b32_e32 v97, v133
	v_mov_b32_e32 v34, v133
	v_mov_b32_e32 v35, v133
	v_mov_b32_e32 v36, v133
	v_mov_b32_e32 v37, v133
	v_mov_b32_e32 v38, v133
	v_mov_b32_e32 v39, v133
	v_mov_b32_e32 v40, v133
	v_mov_b32_e32 v41, v133
	v_mov_b32_e32 v42, v133
	v_mov_b32_e32 v43, v133
	v_mov_b32_e32 v44, v133
	v_mov_b32_e32 v45, v133
	v_mov_b32_e32 v46, v133
	v_mov_b32_e32 v47, v133
	v_mov_b32_e32 v48, v133
	v_mov_b32_e32 v49, v133
	v_mov_b32_e32 v50, v133
	v_mov_b32_e32 v51, v133
	v_mov_b32_e32 v52, v133
	v_mov_b32_e32 v53, v133
	v_mov_b32_e32 v58, v133
	v_mov_b32_e32 v59, v133
	v_mov_b32_e32 v60, v133
	v_mov_b32_e32 v61, v133
	v_mov_b32_e32 v66, v133
	v_mov_b32_e32 v67, v133
	v_mov_b32_e32 v68, v133
	v_mov_b32_e32 v69, v133
	v_mov_b32_e32 v74, v133
	v_mov_b32_e32 v75, v133
	v_mov_b32_e32 v76, v133
	v_mov_b32_e32 v77, v133
	v_mov_b32_e32 v98, v133
	v_mov_b32_e32 v99, v133
	v_mov_b32_e32 v100, v133
	v_mov_b32_e32 v101, v133
	v_mov_b32_e32 v102, v133
	v_mov_b32_e32 v103, v133
	v_mov_b32_e32 v104, v133
	v_mov_b32_e32 v105, v133
	v_mov_b32_e32 v106, v133
	v_mov_b32_e32 v107, v133
	v_mov_b32_e32 v108, v133
	v_mov_b32_e32 v109, v133
	v_mov_b32_e32 v110, v133
	v_mov_b32_e32 v111, v133
	v_mov_b32_e32 v112, v133
	v_mov_b32_e32 v113, v133
	v_mov_b32_e32 v114, v133
	v_mov_b32_e32 v115, v133
	v_mov_b32_e32 v116, v133
	v_mov_b32_e32 v117, v133
	v_mov_b32_e32 v118, v133
	v_mov_b32_e32 v119, v133
	v_mov_b32_e32 v120, v133
	v_mov_b32_e32 v121, v133
	v_mov_b32_e32 v122, v133
	v_mov_b32_e32 v123, v133
	v_mov_b32_e32 v124, v133
	v_mov_b32_e32 v125, v133
	v_mov_b32_e32 v126, v133
	v_mov_b32_e32 v127, v133
	v_mov_b32_e32 v128, v133
	v_mov_b32_e32 v129, v133
	s_barrier

.LBB0_682:
	s_add_u32 s84, s18, 0x2359000
	s_addc_u32 s85, s19, 0
	s_add_u32 s86, s18, 0x2399000
	v_bfe_u32 v156, v6, 4, 2
	s_addc_u32 s87, s19, 0
	v_and_b32_e32 v139, 15, v6
	v_lshlrev_b32_e32 v7, 4, v156
	v_lshlrev_b32_e32 v6, 2, v6
	s_lshl_b32 s0, s0, 5
	v_lshl_or_b32 v7, v139, 6, v7
	s_lshl_b32 s18, s30, 13
	v_and_b32_e32 v6, 32, v6
	s_and_b32 s89, s0, 0x60
	v_bitop3_b32 v8, v7, s18, v6 bitop3:0xde
	s_lshl_b32 s0, s89, 7
	s_mov_b64 s[18:19], 0x80
	v_bitop3_b32 v157, v7, s0, v6 bitop3:0xde
	v_lshl_add_u64 v[6:7], v[2:3], 0, s[18:19]
	s_add_i32 m0, s28, 0x18000
	s_mov_b64 s[52:53], 0x20080
	global_load_lds_dwordx4 v[6:7], off
	v_lshl_add_u64 v[6:7], v[2:3], 0, s[52:53]
	s_add_i32 m0, s28, 0x1a000
	s_add_i32 s90, s28, 0x8000
	global_load_lds_dwordx4 v[6:7], off
	v_lshl_add_u64 v[6:7], v[4:5], 0, s[18:19]
	s_mov_b32 m0, s90
	s_mov_b64 s[54:55], 0x8080
	s_add_i32 s91, s28, 0xa000
	global_load_lds_dwordx4 v[6:7], off
	v_lshl_add_u64 v[4:5], v[4:5], 0, s[54:55]
	s_mov_b32 m0, s91
	s_mov_b64 s[56:57], 0x40080
	global_load_lds_dwordx4 v[4:5], off
	v_lshl_add_u64 v[4:5], v[2:3], 0, s[56:57]
	s_add_i32 m0, s28, 0x1c000
	s_mov_b64 s[58:59], 0x60080
	global_load_lds_dwordx4 v[4:5], off
	v_lshl_add_u64 v[2:3], v[2:3], 0, s[58:59]
	s_add_i32 m0, s28, 0x1e000
	s_lshl_b32 s88, s30, 6
	global_load_lds_dwordx4 v[2:3], off
	s_waitcnt vmcnt(10)
	s_barrier
	s_waitcnt vmcnt(6)
	s_cmpk_lt_u32 s1, 0x100
	v_readlane_b32 s0, v254, 16
	s_cselect_b64 s[60:61], -1, 0
	s_add_i32 s92, s2, s0
	s_add_i32 s95, 0, 0x10000
	s_add_i32 s96, 0, 0x14000
	s_lshl_b32 s93, s92, 8
	s_lshl_b32 s94, s0, 8
	v_add_u32_e32 v158, s95, v157
	v_add_u32_e32 v159, 0, v8
	v_add_u32_e32 v160, s96, v157
	s_mov_b64 s[62:63], 0x100
	s_mov_b64 s[64:65], 0x180
	s_lshl_b32 s50, s89, 1
	s_barrier
	v_readlane_b32 s1, v254, 17
	s_branch .LBB0_685

.LBB0_796:
	v_bfe_u32 v134, v6, 4, 2
	s_lshl_b32 s1, s1, 5
	v_and_b32_e32 v135, 15, v6
	v_lshlrev_b32_e32 v7, 4, v134
	v_lshlrev_b32_e32 v6, 2, v6
	s_and_b32 s26, s1, 0x60
	s_lshl_b32 s25, s7, 6
	v_lshl_or_b32 v7, v135, 6, v7
	s_lshl_b32 s7, s7, 13
	v_and_b32_e32 v6, 32, v6
	s_lshl_b32 s1, s26, 7
	s_mov_b64 s[42:43], 0x80
	v_bitop3_b32 v8, v7, s7, v6 bitop3:0xde
	v_bitop3_b32 v9, v7, s1, v6 bitop3:0xde
	v_lshl_add_u64 v[6:7], v[2:3], 0, s[42:43]
	s_add_i32 m0, s5, 0x18000
	s_mov_b64 s[44:45], 0x8080
	global_load_lds_dwordx4 v[6:7], off
	v_lshl_add_u64 v[6:7], v[2:3], 0, s[44:45]
	s_add_i32 m0, s5, 0x1a000
	s_add_i32 s29, s5, 0x8000
	global_load_lds_dwordx4 v[6:7], off
	v_lshl_add_u64 v[6:7], v[4:5], 0, s[42:43]
	s_mov_b32 m0, s29
	s_add_i32 s33, s5, 0xa000
	global_load_lds_dwordx4 v[6:7], off
	v_lshl_add_u64 v[4:5], v[4:5], 0, s[44:45]
	s_mov_b32 m0, s33
	s_mov_b64 s[46:47], 0x10080
	global_load_lds_dwordx4 v[4:5], off
	v_lshl_add_u64 v[4:5], v[2:3], 0, s[46:47]
	s_add_i32 m0, s5, 0x1c000
	s_mov_b64 s[48:49], 0x18080
	global_load_lds_dwordx4 v[4:5], off
	v_lshl_add_u64 v[2:3], v[2:3], 0, s[48:49]
	s_add_i32 m0, s5, 0x1e000
	s_add_i32 s8, 0, 0x10000
	global_load_lds_dwordx4 v[2:3], off
	s_waitcnt vmcnt(10)
	s_barrier
	s_waitcnt vmcnt(6)
	s_add_i32 s7, 0, 0x14000
	s_add_i32 s9, 0, 0x18000
	s_add_i32 s24, 0, 0x1c000
	s_add_i32 s39, s8, s0
	s_add_i32 s41, s7, s0
	s_add_i32 s59, s9, s0
	s_add_i32 s61, s24, s0
	s_mov_b64 s[54:55], 0
	s_mov_b64 s[50:51], -1
	s_mov_b64 s[52:53], 0x100
	s_add_i32 s35, s5, 0xc000
	s_add_i32 s38, s5, 0xe000
	s_add_i32 s40, s39, 0x2000
	s_add_i32 s58, s41, 0x2000
	s_add_i32 s60, s59, 0x2000
	s_add_i32 s62, s61, 0x2000
	v_add_u32_e32 v136, s8, v9
	v_add_u32_e32 v137, 0, v8
	v_add_u32_e32 v139, s7, v9
	v_add_u32_e32 v140, s9, v9
	v_add_u32_e32 v141, s24, v9
	v_mov_b32_e32 v2, v133
	v_mov_b32_e32 v3, v133
	v_mov_b32_e32 v4, v133
	v_mov_b32_e32 v5, v133
	v_mov_b32_e32 v6, v133
	v_mov_b32_e32 v7, v133
	v_mov_b32_e32 v8, v133
	v_mov_b32_e32 v9, v133
	v_mov_b32_e32 v10, v133
	v_mov_b32_e32 v11, v133
	v_mov_b32_e32 v12, v133
	v_mov_b32_e32 v13, v133
	v_mov_b32_e32 v14, v133
	v_mov_b32_e32 v15, v133
	v_mov_b32_e32 v16, v133
	v_mov_b32_e32 v17, v133
	v_mov_b32_e32 v18, v133
	v_mov_b32_e32 v19, v133
	v_mov_b32_e32 v20, v133
	v_mov_b32_e32 v21, v133
	v_mov_b32_e32 v22, v133
	v_mov_b32_e32 v23, v133
	v_mov_b32_e32 v24, v133
	v_mov_b32_e32 v25, v133
	v_mov_b32_e32 v26, v133
	v_mov_b32_e32 v27, v133
	v_mov_b32_e32 v28, v133
	v_mov_b32_e32 v29, v133
	v_mov_b32_e32 v30, v133
	v_mov_b32_e32 v31, v133
	v_mov_b32_e32 v32, v133
	v_mov_b32_e32 v33, v133
	v_mov_b32_e32 v54, v133
	v_mov_b32_e32 v55, v133
	v_mov_b32_e32 v56, v133
	v_mov_b32_e32 v57, v133
	v_mov_b32_e32 v62, v133
	v_mov_b32_e32 v63, v133
	v_mov_b32_e32 v64, v133
	v_mov_b32_e32 v65, v133
	v_mov_b32_e32 v74, v133
	v_mov_b32_e32 v75, v133
	v_mov_b32_e32 v76, v133
	v_mov_b32_e32 v77, v133
	v_mov_b32_e32 v78, v133
	v_mov_b32_e32 v79, v133
	v_mov_b32_e32 v80, v133
	v_mov_b32_e32 v81, v133
	v_mov_b32_e32 v82, v133
	v_mov_b32_e32 v83, v133
	v_mov_b32_e32 v84, v133
	v_mov_b32_e32 v85, v133
	v_mov_b32_e32 v86, v133
	v_mov_b32_e32 v87, v133
	v_mov_b32_e32 v88, v133
	v_mov_b32_e32 v89, v133
	v_mov_b32_e32 v90, v133
	v_mov_b32_e32 v91, v133
	v_mov_b32_e32 v92, v133
	v_mov_b32_e32 v93, v133
	v_mov_b32_e32 v94, v133
	v_mov_b32_e32 v95, v133
	v_mov_b32_e32 v96, v133
	v_mov_b32_e32 v97, v133
	v_mov_b32_e32 v34, v133
	v_mov_b32_e32 v35, v133
	v_mov_b32_e32 v36, v133
	v_mov_b32_e32 v37, v133
	v_mov_b32_e32 v38, v133
	v_mov_b32_e32 v39, v133
	v_mov_b32_e32 v40, v133
	v_mov_b32_e32 v41, v133
	v_mov_b32_e32 v42, v133
	v_mov_b32_e32 v43, v133
	v_mov_b32_e32 v44, v133
	v_mov_b32_e32 v45, v133
	v_mov_b32_e32 v46, v133
	v_mov_b32_e32 v47, v133
	v_mov_b32_e32 v48, v133
	v_mov_b32_e32 v49, v133
	v_mov_b32_e32 v50, v133
	v_mov_b32_e32 v51, v133
	v_mov_b32_e32 v52, v133
	v_mov_b32_e32 v53, v133
	v_mov_b32_e32 v58, v133
	v_mov_b32_e32 v59, v133
	v_mov_b32_e32 v60, v133
	v_mov_b32_e32 v61, v133
	v_mov_b32_e32 v66, v133
	v_mov_b32_e32 v67, v133
	v_mov_b32_e32 v68, v133
	v_mov_b32_e32 v69, v133
	v_mov_b32_e32 v70, v133
	v_mov_b32_e32 v71, v133
	v_mov_b32_e32 v72, v133
	v_mov_b32_e32 v73, v133
	v_mov_b32_e32 v98, v133
	v_mov_b32_e32 v99, v133
	v_mov_b32_e32 v100, v133
	v_mov_b32_e32 v101, v133
	v_mov_b32_e32 v102, v133
	v_mov_b32_e32 v103, v133
	v_mov_b32_e32 v104, v133
	v_mov_b32_e32 v105, v133
	v_mov_b32_e32 v106, v133
	v_mov_b32_e32 v107, v133
	v_mov_b32_e32 v108, v133
	v_mov_b32_e32 v109, v133
	v_mov_b32_e32 v110, v133
	v_mov_b32_e32 v111, v133
	v_mov_b32_e32 v112, v133
	v_mov_b32_e32 v113, v133
	v_mov_b32_e32 v114, v133
	v_mov_b32_e32 v115, v133
	v_mov_b32_e32 v116, v133
	v_mov_b32_e32 v117, v133
	v_mov_b32_e32 v118, v133
	v_mov_b32_e32 v119, v133
	v_mov_b32_e32 v120, v133
	v_mov_b32_e32 v121, v133
	v_mov_b32_e32 v122, v133
	v_mov_b32_e32 v123, v133
	v_mov_b32_e32 v124, v133
	v_mov_b32_e32 v125, v133
	v_mov_b32_e32 v126, v133
	v_mov_b32_e32 v127, v133
	v_mov_b32_e32 v128, v133
	v_mov_b32_e32 v129, v133
	s_barrier

.LBB0_802:
	s_mov_b64 s[16:17], 0x80
	s_add_i32 s20, s9, s29
	v_lshl_add_u64 v[10:11], v[26:27], 0, s[16:17]
	s_mov_b32 m0, s20
	s_mov_b64 s[30:31], 0x20080
	s_add_i32 s23, s20, 0x2000
	global_load_lds_dwordx4 v[10:11], off
	v_lshl_add_u64 v[16:17], v[26:27], 0, s[30:31]
	s_mov_b32 m0, s23
	s_add_i32 s18, s25, 0x8000
	global_load_lds_dwordx4 v[16:17], off
	v_lshl_add_u64 v[6:7], v[22:23], 0, s[16:17]
	s_mov_b32 m0, s18
	s_add_i32 s19, s25, 0xa000
	global_load_lds_dwordx4 v[6:7], off
	v_lshl_add_u64 v[8:9], v[22:23], 0, s[30:31]
	s_mov_b32 m0, s19
	s_mov_b64 s[30:31], 0x40080
	s_add_i32 s16, s24, s29
	global_load_lds_dwordx4 v[8:9], off
	v_lshl_add_u64 v[2:3], v[26:27], 0, s[30:31]
	s_mov_b32 m0, s16
	s_mov_b64 s[38:39], 0x60080
	s_add_i32 s17, s16, 0x2000
	global_load_lds_dwordx4 v[2:3], off
	v_lshl_add_u64 v[4:5], v[26:27], 0, s[38:39]
	s_mov_b32 m0, s17
	v_bfe_u32 v131, v30, 4, 2
	global_load_lds_dwordx4 v[4:5], off
	s_waitcnt vmcnt(10)
	s_barrier
	v_and_b32_e32 v132, 15, v30
	v_lshlrev_b32_e32 v31, 4, v131
	v_lshlrev_b32_e32 v30, 2, v30
	s_and_b32 s6, s1, 3
	s_lshl_b32 s1, s27, 6
	v_lshl_or_b32 v31, v132, 6, v31
	s_lshl_b32 s27, s27, 13
	v_and_b32_e32 v30, 32, v30
	v_bitop3_b32 v32, v31, s27, v30 bitop3:0xde
	s_lshl_b32 s27, s6, 12
	v_bitop3_b32 v30, v31, s27, v30 bitop3:0xde
	v_add_u32_e32 v130, s8, v30
	s_waitcnt vmcnt(6)
	s_barrier
	v_add_u32_e32 v133, 0, v32
	v_add_u32_e32 v139, s7, v30
	v_add_u32_e32 v230, s9, v30
	v_add_u32_e32 v236, s24, v30
	ds_read_b128 v[30:33], v130
	ds_read_b128 v[34:37], v130 offset:1024
	ds_read_b128 v[38:41], v130 offset:2048
	ds_read_b128 v[42:45], v130 offset:3072
	s_add_i32 s9, s8, s29
	s_add_i32 s8, s7, s29
	s_add_i32 s28, s25, 0xc000
	s_add_i32 s27, s25, 0xe000
	s_add_i32 s24, s9, 0x2000
	s_add_i32 s7, s8, 0x2000
	s_cmpk_gt_u32 s0, 0xff
	s_mov_b32 m0, s28
	v_lshl_add_u64 v[78:79], v[22:23], 0, s[30:31]
	ds_read_b128 v[46:49], v133
	ds_read_b128 v[50:53], v133 offset:1024
	ds_read_b128 v[54:57], v133 offset:2048
	ds_read_b128 v[58:61], v133 offset:3072
	ds_read_b128 v[62:65], v133 offset:4096
	ds_read_b128 v[66:69], v133 offset:5120
	ds_read_b128 v[70:73], v133 offset:6144
	ds_read_b128 v[74:77], v133 offset:7168
	global_load_lds_dwordx4 v[78:79], off
	v_lshl_add_u64 v[78:79], v[22:23], 0, s[38:39]
	s_mov_b32 m0, s27
	s_nop 0
	global_load_lds_dwordx4 v[78:79], off
	s_waitcnt lgkmcnt(8)
	s_barrier
	s_waitcnt lgkmcnt(0)
	s_setprio 1
	s_waitcnt lgkmcnt(0)
	v_mfma_f32_16x16x32_bf16 v[78:81], v[30:33], v[46:49], 0
	v_mfma_f32_16x16x32_bf16 v[82:85], v[38:41], v[46:49], 0
	v_mfma_f32_16x16x32_bf16 v[86:89], v[30:33], v[54:57], 0
	v_mfma_f32_16x16x32_bf16 v[90:93], v[38:41], v[54:57], 0
	v_mfma_f32_16x16x32_bf16 v[94:97], v[30:33], v[62:65], 0
	v_mfma_f32_16x16x32_bf16 v[98:101], v[38:41], v[62:65], 0
	v_mfma_f32_16x16x32_bf16 v[102:105], v[30:33], v[70:73], 0
	v_mfma_f32_16x16x32_bf16 v[106:109], v[38:41], v[70:73], 0
	v_mfma_f32_16x16x32_bf16 v[78:81], v[34:37], v[50:53], v[78:81]
	v_mfma_f32_16x16x32_bf16 v[82:85], v[42:45], v[50:53], v[82:85]
	v_mfma_f32_16x16x32_bf16 v[86:89], v[34:37], v[58:61], v[86:89]
	v_mfma_f32_16x16x32_bf16 v[90:93], v[42:45], v[58:61], v[90:93]
	v_mfma_f32_16x16x32_bf16 v[94:97], v[34:37], v[66:69], v[94:97]
	v_mfma_f32_16x16x32_bf16 v[98:101], v[42:45], v[66:69], v[98:101]
	v_mfma_f32_16x16x32_bf16 v[102:105], v[34:37], v[74:77], v[102:105]
	v_mfma_f32_16x16x32_bf16 v[106:109], v[42:45], v[74:77], v[106:109]
	s_setprio 0
	s_barrier
	s_mov_b64 s[30:31], 0x100
	s_mov_b32 m0, s9
	v_lshl_add_u64 v[126:127], v[26:27], 0, s[30:31]
	s_mov_b64 s[38:39], 0x20100
	ds_read_b128 v[110:113], v139
	ds_read_b128 v[114:117], v139 offset:1024
	ds_read_b128 v[118:121], v139 offset:2048
	ds_read_b128 v[122:125], v139 offset:3072
	global_load_lds_dwordx4 v[126:127], off
	v_lshl_add_u64 v[126:127], v[26:27], 0, s[38:39]
	s_mov_b32 m0, s24
	s_nop 0
	global_load_lds_dwordx4 v[126:127], off
	s_barrier
	s_waitcnt lgkmcnt(0)
	s_setprio 1
	s_waitcnt lgkmcnt(0)
	v_mfma_f32_16x16x32_bf16 v[126:129], v[110:113], v[46:49], 0
	v_mfma_f32_16x16x32_bf16 v[46:49], v[118:121], v[46:49], 0
	v_mfma_f32_16x16x32_bf16 v[126:129], v[114:117], v[50:53], v[126:129]
	v_mfma_f32_16x16x32_bf16 v[46:49], v[122:125], v[50:53], v[46:49]
	v_mfma_f32_16x16x32_bf16 v[50:53], v[110:113], v[54:57], 0
	v_mfma_f32_16x16x32_bf16 v[54:57], v[118:121], v[54:57], 0
	v_mfma_f32_16x16x32_bf16 v[50:53], v[114:117], v[58:61], v[50:53]
	v_mfma_f32_16x16x32_bf16 v[54:57], v[122:125], v[58:61], v[54:57]
	v_mfma_f32_16x16x32_bf16 v[58:61], v[110:113], v[62:65], 0
	v_mfma_f32_16x16x32_bf16 v[62:65], v[118:121], v[62:65], 0
	v_mfma_f32_16x16x32_bf16 v[58:61], v[114:117], v[66:69], v[58:61]
	v_mfma_f32_16x16x32_bf16 v[62:65], v[122:125], v[66:69], v[62:65]
	v_mfma_f32_16x16x32_bf16 v[66:69], v[110:113], v[70:73], 0
	v_mfma_f32_16x16x32_bf16 v[70:73], v[118:121], v[70:73], 0
	v_mfma_f32_16x16x32_bf16 v[66:69], v[114:117], v[74:77], v[66:69]
	v_mfma_f32_16x16x32_bf16 v[70:73], v[122:125], v[74:77], v[70:73]
	s_setprio 0
	s_mov_b32 m0, s25
	v_lshl_add_u64 v[164:165], v[22:23], 0, s[30:31]
	s_barrier
	ds_read_b128 v[74:77], v133 offset:16384
	ds_read_b128 v[134:137], v133 offset:17408
	ds_read_b128 v[140:143], v133 offset:18432
	ds_read_b128 v[144:147], v133 offset:19456
	ds_read_b128 v[148:151], v133 offset:20480
	ds_read_b128 v[152:155], v133 offset:21504
	ds_read_b128 v[156:159], v133 offset:22528
	ds_read_b128 v[160:163], v133 offset:23552
	global_load_lds_dwordx4 v[164:165], off
	v_lshl_add_u64 v[164:165], v[22:23], 0, s[38:39]
	s_mov_b32 m0, s26
	s_nop 0
	global_load_lds_dwordx4 v[164:165], off
	s_barrier
	s_waitcnt lgkmcnt(0)
	s_setprio 1
	s_waitcnt lgkmcnt(0)
	v_mfma_f32_16x16x32_bf16 v[164:167], v[30:33], v[74:77], 0
	v_mfma_f32_16x16x32_bf16 v[172:175], v[30:33], v[140:143], 0
	v_mfma_f32_16x16x32_bf16 v[180:183], v[30:33], v[148:151], 0
	v_mfma_f32_16x16x32_bf16 v[30:33], v[30:33], v[156:159], 0
	v_mfma_f32_16x16x32_bf16 v[164:167], v[34:37], v[134:137], v[164:167]
	v_mfma_f32_16x16x32_bf16 v[172:175], v[34:37], v[144:147], v[172:175]
	v_mfma_f32_16x16x32_bf16 v[180:183], v[34:37], v[152:155], v[180:183]
	v_mfma_f32_16x16x32_bf16 v[30:33], v[34:37], v[160:163], v[30:33]
	v_mfma_f32_16x16x32_bf16 v[34:37], v[38:41], v[156:159], 0
	v_mfma_f32_16x16x32_bf16 v[168:171], v[38:41], v[74:77], 0
	v_mfma_f32_16x16x32_bf16 v[176:179], v[38:41], v[140:143], 0
	v_mfma_f32_16x16x32_bf16 v[184:187], v[38:41], v[148:151], 0
	v_mfma_f32_16x16x32_bf16 v[34:37], v[42:45], v[160:163], v[34:37]
	v_mfma_f32_16x16x32_bf16 v[168:171], v[42:45], v[134:137], v[168:171]
	v_mfma_f32_16x16x32_bf16 v[176:179], v[42:45], v[144:147], v[176:179]
	v_mfma_f32_16x16x32_bf16 v[184:187], v[42:45], v[152:155], v[184:187]
	s_setprio 0
	s_barrier
	s_mov_b64 s[30:31], 0x40100
	s_mov_b32 m0, s8
	v_lshl_add_u64 v[38:39], v[26:27], 0, s[30:31]
	s_mov_b64 s[38:39], 0x60100
	global_load_lds_dwordx4 v[38:39], off
	v_lshl_add_u64 v[38:39], v[26:27], 0, s[38:39]
	s_mov_b32 m0, s7
	s_nop 0
	global_load_lds_dwordx4 v[38:39], off
	s_waitcnt vmcnt(6)
	s_barrier
	s_setprio 1
	v_mfma_f32_16x16x32_bf16 v[38:41], v[110:113], v[74:77], 0
	v_mfma_f32_16x16x32_bf16 v[42:45], v[118:121], v[74:77], 0
	v_mfma_f32_16x16x32_bf16 v[38:41], v[114:117], v[134:137], v[38:41]
	v_mfma_f32_16x16x32_bf16 v[42:45], v[122:125], v[134:137], v[42:45]
	v_mfma_f32_16x16x32_bf16 v[74:77], v[110:113], v[140:143], 0
	v_mfma_f32_16x16x32_bf16 v[134:137], v[118:121], v[140:143], 0
	v_mfma_f32_16x16x32_bf16 v[140:143], v[110:113], v[148:151], 0
	v_mfma_f32_16x16x32_bf16 v[110:113], v[110:113], v[156:159], 0
	v_mfma_f32_16x16x32_bf16 v[74:77], v[114:117], v[144:147], v[74:77]
	v_mfma_f32_16x16x32_bf16 v[140:143], v[114:117], v[152:155], v[140:143]
	v_mfma_f32_16x16x32_bf16 v[110:113], v[114:117], v[160:163], v[110:113]
	v_mfma_f32_16x16x32_bf16 v[114:117], v[118:121], v[156:159], 0
	v_mfma_f32_16x16x32_bf16 v[134:137], v[122:125], v[144:147], v[134:137]
	v_mfma_f32_16x16x32_bf16 v[144:147], v[118:121], v[148:151], 0
	v_mfma_f32_16x16x32_bf16 v[114:117], v[122:125], v[160:163], v[114:117]
	v_mfma_f32_16x16x32_bf16 v[144:147], v[122:125], v[152:155], v[144:147]
	s_setprio 0
	s_barrier
	ds_read_b128 v[118:121], v230
	ds_read_b128 v[122:125], v230 offset:1024
	ds_read_b128 v[148:151], v230 offset:2048
	ds_read_b128 v[152:155], v230 offset:3072
	s_mov_b32 m0, s21
	v_lshl_add_u64 v[212:213], v[22:23], 0, s[30:31]
	ds_read_b128 v[156:159], v133 offset:32768
	ds_read_b128 v[160:163], v133 offset:33792
	ds_read_b128 v[188:191], v133 offset:34816
	ds_read_b128 v[192:195], v133 offset:35840
	ds_read_b128 v[196:199], v133 offset:36864
	ds_read_b128 v[200:203], v133 offset:37888
	ds_read_b128 v[204:207], v133 offset:38912
	ds_read_b128 v[208:211], v133 offset:39936
	global_load_lds_dwordx4 v[212:213], off
	v_lshl_add_u64 v[212:213], v[22:23], 0, s[38:39]
	s_mov_b32 m0, s22
	s_nop 0
	global_load_lds_dwordx4 v[212:213], off
	s_waitcnt lgkmcnt(8)
	s_barrier
	s_waitcnt lgkmcnt(0)
	s_setprio 1
	s_waitcnt lgkmcnt(0)
	v_mfma_f32_16x16x32_bf16 v[78:81], v[118:121], v[156:159], v[78:81]
	v_mfma_f32_16x16x32_bf16 v[82:85], v[148:151], v[156:159], v[82:85]
	v_mfma_f32_16x16x32_bf16 v[86:89], v[118:121], v[188:191], v[86:89]
	v_mfma_f32_16x16x32_bf16 v[90:93], v[148:151], v[188:191], v[90:93]
	v_mfma_f32_16x16x32_bf16 v[94:97], v[118:121], v[196:199], v[94:97]
	v_mfma_f32_16x16x32_bf16 v[98:101], v[148:151], v[196:199], v[98:101]
	v_mfma_f32_16x16x32_bf16 v[102:105], v[118:121], v[204:207], v[102:105]
	v_mfma_f32_16x16x32_bf16 v[106:109], v[148:151], v[204:207], v[106:109]
	v_mfma_f32_16x16x32_bf16 v[78:81], v[122:125], v[160:163], v[78:81]
	v_mfma_f32_16x16x32_bf16 v[82:85], v[152:155], v[160:163], v[82:85]
	v_mfma_f32_16x16x32_bf16 v[86:89], v[122:125], v[192:195], v[86:89]
	v_mfma_f32_16x16x32_bf16 v[90:93], v[152:155], v[192:195], v[90:93]
	v_mfma_f32_16x16x32_bf16 v[94:97], v[122:125], v[200:203], v[94:97]
	v_mfma_f32_16x16x32_bf16 v[98:101], v[152:155], v[200:203], v[98:101]
	v_mfma_f32_16x16x32_bf16 v[102:105], v[122:125], v[208:211], v[102:105]
	v_mfma_f32_16x16x32_bf16 v[106:109], v[152:155], v[208:211], v[106:109]
	s_setprio 0
	s_barrier
	s_mov_b64 s[30:31], 0x180
	s_mov_b32 m0, s20
	v_lshl_add_u64 v[228:229], v[26:27], 0, s[30:31]
	s_mov_b64 s[38:39], 0x20180
	ds_read_b128 v[212:215], v236
	ds_read_b128 v[216:219], v236 offset:1024
	ds_read_b128 v[220:223], v236 offset:2048
	ds_read_b128 v[224:227], v236 offset:3072
	global_load_lds_dwordx4 v[228:229], off
	v_lshl_add_u64 v[228:229], v[26:27], 0, s[38:39]
	s_mov_b32 m0, s23
	s_nop 0
	global_load_lds_dwordx4 v[228:229], off
	s_barrier
	s_waitcnt lgkmcnt(0)
	s_setprio 1
	s_waitcnt lgkmcnt(0)
	v_mfma_f32_16x16x32_bf16 v[126:129], v[212:215], v[156:159], v[126:129]
	v_mfma_f32_16x16x32_bf16 v[46:49], v[220:223], v[156:159], v[46:49]
	v_mfma_f32_16x16x32_bf16 v[50:53], v[212:215], v[188:191], v[50:53]
	v_mfma_f32_16x16x32_bf16 v[54:57], v[220:223], v[188:191], v[54:57]
	v_mfma_f32_16x16x32_bf16 v[58:61], v[212:215], v[196:199], v[58:61]
	v_mfma_f32_16x16x32_bf16 v[62:65], v[220:223], v[196:199], v[62:65]
	v_mfma_f32_16x16x32_bf16 v[66:69], v[212:215], v[204:207], v[66:69]
	v_mfma_f32_16x16x32_bf16 v[70:73], v[220:223], v[204:207], v[70:73]
	v_mfma_f32_16x16x32_bf16 v[126:129], v[216:219], v[160:163], v[126:129]
	v_mfma_f32_16x16x32_bf16 v[46:49], v[224:227], v[160:163], v[46:49]
	v_mfma_f32_16x16x32_bf16 v[50:53], v[216:219], v[192:195], v[50:53]
	v_mfma_f32_16x16x32_bf16 v[54:57], v[224:227], v[192:195], v[54:57]
	v_mfma_f32_16x16x32_bf16 v[58:61], v[216:219], v[200:203], v[58:61]
	v_mfma_f32_16x16x32_bf16 v[62:65], v[224:227], v[200:203], v[62:65]
	v_mfma_f32_16x16x32_bf16 v[66:69], v[216:219], v[208:211], v[66:69]
	v_mfma_f32_16x16x32_bf16 v[70:73], v[224:227], v[208:211], v[70:73]
	s_setprio 0
	s_mov_b32 m0, s18
	v_lshl_add_u64 v[228:229], v[22:23], 0, s[30:31]
	s_barrier
	ds_read_b128 v[156:159], v133 offset:49152
	ds_read_b128 v[160:163], v133 offset:50176
	ds_read_b128 v[188:191], v133 offset:51200
	ds_read_b128 v[192:195], v133 offset:52224
	ds_read_b128 v[196:199], v133 offset:53248
	ds_read_b128 v[200:203], v133 offset:54272
	ds_read_b128 v[204:207], v133 offset:55296
	ds_read_b128 v[208:211], v133 offset:56320
	global_load_lds_dwordx4 v[228:229], off
	v_lshl_add_u64 v[228:229], v[22:23], 0, s[38:39]
	s_mov_b32 m0, s19
	s_nop 0
	global_load_lds_dwordx4 v[228:229], off
	s_barrier
	s_waitcnt lgkmcnt(0)
	s_setprio 1
	s_waitcnt lgkmcnt(0)
	v_mfma_f32_16x16x32_bf16 v[30:33], v[118:121], v[204:207], v[30:33]
	v_mfma_f32_16x16x32_bf16 v[34:37], v[148:151], v[204:207], v[34:37]
	v_mfma_f32_16x16x32_bf16 v[164:167], v[118:121], v[156:159], v[164:167]
	v_mfma_f32_16x16x32_bf16 v[168:171], v[148:151], v[156:159], v[168:171]
	v_mfma_f32_16x16x32_bf16 v[172:175], v[118:121], v[188:191], v[172:175]
	v_mfma_f32_16x16x32_bf16 v[176:179], v[148:151], v[188:191], v[176:179]
	v_mfma_f32_16x16x32_bf16 v[180:183], v[118:121], v[196:199], v[180:183]
	v_mfma_f32_16x16x32_bf16 v[184:187], v[148:151], v[196:199], v[184:187]
	v_mfma_f32_16x16x32_bf16 v[30:33], v[122:125], v[208:211], v[30:33]
	v_mfma_f32_16x16x32_bf16 v[34:37], v[152:155], v[208:211], v[34:37]
	v_mfma_f32_16x16x32_bf16 v[164:167], v[122:125], v[160:163], v[164:167]
	v_mfma_f32_16x16x32_bf16 v[168:171], v[152:155], v[160:163], v[168:171]
	v_mfma_f32_16x16x32_bf16 v[172:175], v[122:125], v[192:195], v[172:175]
	v_mfma_f32_16x16x32_bf16 v[176:179], v[152:155], v[192:195], v[176:179]
	v_mfma_f32_16x16x32_bf16 v[180:183], v[122:125], v[200:203], v[180:183]
	v_mfma_f32_16x16x32_bf16 v[184:187], v[152:155], v[200:203], v[184:187]
	s_setprio 0
	s_barrier
	s_mov_b64 s[30:31], 0x40180
	s_mov_b32 m0, s16
	v_lshl_add_u64 v[118:119], v[26:27], 0, s[30:31]
	s_mov_b64 s[38:39], 0x60180
	global_load_lds_dwordx4 v[118:119], off
	v_lshl_add_u64 v[118:119], v[26:27], 0, s[38:39]
	s_mov_b32 m0, s17
	s_nop 0
	global_load_lds_dwordx4 v[118:119], off
	s_waitcnt vmcnt(6)
	s_barrier
	s_setprio 1
	v_mfma_f32_16x16x32_bf16 v[38:41], v[212:215], v[156:159], v[38:41]
	v_mfma_f32_16x16x32_bf16 v[42:45], v[220:223], v[156:159], v[42:45]
	v_mfma_f32_16x16x32_bf16 v[74:77], v[212:215], v[188:191], v[74:77]
	v_mfma_f32_16x16x32_bf16 v[118:121], v[220:223], v[188:191], v[134:137]
	v_mfma_f32_16x16x32_bf16 v[122:125], v[212:215], v[196:199], v[140:143]
	v_mfma_f32_16x16x32_bf16 v[110:113], v[212:215], v[204:207], v[110:113]
	v_mfma_f32_16x16x32_bf16 v[114:117], v[220:223], v[204:207], v[114:117]
	v_mfma_f32_16x16x32_bf16 v[38:41], v[216:219], v[160:163], v[38:41]
	v_mfma_f32_16x16x32_bf16 v[42:45], v[224:227], v[160:163], v[42:45]
	v_mfma_f32_16x16x32_bf16 v[74:77], v[216:219], v[192:195], v[74:77]
	v_mfma_f32_16x16x32_bf16 v[118:121], v[224:227], v[192:195], v[118:121]
	v_mfma_f32_16x16x32_bf16 v[122:125], v[216:219], v[200:203], v[122:125]
	v_mfma_f32_16x16x32_bf16 v[134:137], v[220:223], v[196:199], v[144:147]
	v_mfma_f32_16x16x32_bf16 v[110:113], v[216:219], v[208:211], v[110:113]
	v_mfma_f32_16x16x32_bf16 v[114:117], v[224:227], v[208:211], v[114:117]
	v_mfma_f32_16x16x32_bf16 v[134:137], v[224:227], v[200:203], v[134:137]
	s_setprio 0
	s_barrier
	ds_read_b128 v[140:143], v130
	ds_read_b128 v[144:147], v130 offset:1024
	ds_read_b128 v[148:151], v130 offset:2048
	ds_read_b128 v[152:155], v130 offset:3072
	s_mov_b32 m0, s28
	v_lshl_add_u64 v[212:213], v[22:23], 0, s[30:31]
	ds_read_b128 v[156:159], v133
	ds_read_b128 v[160:163], v133 offset:1024
	ds_read_b128 v[188:191], v133 offset:2048
	ds_read_b128 v[192:195], v133 offset:3072
	ds_read_b128 v[196:199], v133 offset:4096
	ds_read_b128 v[200:203], v133 offset:5120
	ds_read_b128 v[204:207], v133 offset:6144
	ds_read_b128 v[208:211], v133 offset:7168
	global_load_lds_dwordx4 v[212:213], off
	v_lshl_add_u64 v[212:213], v[22:23], 0, s[38:39]
	s_mov_b32 m0, s27
	s_nop 0
	global_load_lds_dwordx4 v[212:213], off
	s_waitcnt lgkmcnt(8)
	s_barrier
	s_waitcnt lgkmcnt(0)
	s_setprio 1
	s_waitcnt lgkmcnt(0)
	v_mfma_f32_16x16x32_bf16 v[78:81], v[140:143], v[156:159], v[78:81]
	v_mfma_f32_16x16x32_bf16 v[82:85], v[148:151], v[156:159], v[82:85]
	v_mfma_f32_16x16x32_bf16 v[86:89], v[140:143], v[188:191], v[86:89]
	v_mfma_f32_16x16x32_bf16 v[90:93], v[148:151], v[188:191], v[90:93]
	v_mfma_f32_16x16x32_bf16 v[94:97], v[140:143], v[196:199], v[94:97]
	v_mfma_f32_16x16x32_bf16 v[98:101], v[148:151], v[196:199], v[98:101]
	v_mfma_f32_16x16x32_bf16 v[102:105], v[140:143], v[204:207], v[102:105]
	v_mfma_f32_16x16x32_bf16 v[78:81], v[144:147], v[160:163], v[78:81]
	v_mfma_f32_16x16x32_bf16 v[82:85], v[152:155], v[160:163], v[82:85]
	v_mfma_f32_16x16x32_bf16 v[86:89], v[144:147], v[192:195], v[86:89]
	v_mfma_f32_16x16x32_bf16 v[90:93], v[152:155], v[192:195], v[90:93]
	v_mfma_f32_16x16x32_bf16 v[94:97], v[144:147], v[200:203], v[94:97]
	v_mfma_f32_16x16x32_bf16 v[98:101], v[152:155], v[200:203], v[98:101]
	v_mfma_f32_16x16x32_bf16 v[102:105], v[144:147], v[208:211], v[102:105]
	v_mfma_f32_16x16x32_bf16 v[106:109], v[148:151], v[204:207], v[106:109]
	v_mfma_f32_16x16x32_bf16 v[212:215], v[152:155], v[208:211], v[106:109]
	s_setprio 0
	s_barrier
	s_mov_b32 m0, s9
	s_nop 3
	ds_read_b128 v[106:109], v139
	ds_read_b128 v[216:219], v139 offset:1024
	ds_read_b128 v[220:223], v139 offset:2048
	ds_read_b128 v[224:227], v139 offset:3072
	global_load_lds_dwordx4 v[26:27], off
	s_mov_b32 m0, s24
	s_nop 0
	global_load_lds_dwordx4 v[28:29], off
	s_barrier
	s_waitcnt lgkmcnt(0)
	s_setprio 1
	s_waitcnt lgkmcnt(0)
	v_mfma_f32_16x16x32_bf16 v[26:29], v[106:109], v[156:159], v[126:129]
	v_mfma_f32_16x16x32_bf16 v[46:49], v[220:223], v[156:159], v[46:49]
	v_mfma_f32_16x16x32_bf16 v[50:53], v[106:109], v[188:191], v[50:53]
	v_mfma_f32_16x16x32_bf16 v[54:57], v[220:223], v[188:191], v[54:57]
	v_mfma_f32_16x16x32_bf16 v[58:61], v[106:109], v[196:199], v[58:61]
	v_mfma_f32_16x16x32_bf16 v[62:65], v[220:223], v[196:199], v[62:65]
	v_mfma_f32_16x16x32_bf16 v[66:69], v[106:109], v[204:207], v[66:69]
	v_mfma_f32_16x16x32_bf16 v[26:29], v[216:219], v[160:163], v[26:29]
	v_mfma_f32_16x16x32_bf16 v[46:49], v[224:227], v[160:163], v[46:49]
	v_mfma_f32_16x16x32_bf16 v[50:53], v[216:219], v[192:195], v[50:53]
	v_mfma_f32_16x16x32_bf16 v[54:57], v[224:227], v[192:195], v[54:57]
	v_mfma_f32_16x16x32_bf16 v[58:61], v[216:219], v[200:203], v[58:61]
	v_mfma_f32_16x16x32_bf16 v[62:65], v[224:227], v[200:203], v[62:65]
	v_mfma_f32_16x16x32_bf16 v[66:69], v[216:219], v[208:211], v[66:69]
	v_mfma_f32_16x16x32_bf16 v[70:73], v[220:223], v[204:207], v[70:73]
	v_mfma_f32_16x16x32_bf16 v[156:159], v[224:227], v[208:211], v[70:73]
	s_setprio 0
	s_mov_b32 m0, s25
	s_barrier
	s_nop 3
	ds_read_b128 v[70:73], v133 offset:16384
	ds_read_b128 v[126:129], v133 offset:17408
	ds_read_b128 v[160:163], v133 offset:18432
	ds_read_b128 v[188:191], v133 offset:19456
	ds_read_b128 v[192:195], v133 offset:20480
	ds_read_b128 v[196:199], v133 offset:21504
	ds_read_b128 v[200:203], v133 offset:22528
	ds_read_b128 v[204:207], v133 offset:23552
	global_load_lds_dwordx4 v[22:23], off
	s_mov_b32 m0, s26
	s_nop 0
	global_load_lds_dwordx4 v[24:25], off
	s_barrier
	s_waitcnt lgkmcnt(0)
	s_setprio 1
	s_waitcnt lgkmcnt(0)
	v_mfma_f32_16x16x32_bf16 v[30:33], v[140:143], v[200:203], v[30:33]
	v_mfma_f32_16x16x32_bf16 v[22:25], v[140:143], v[70:73], v[164:167]
	v_mfma_f32_16x16x32_bf16 v[164:167], v[148:151], v[70:73], v[168:171]
	v_mfma_f32_16x16x32_bf16 v[168:171], v[140:143], v[160:163], v[172:175]
	v_mfma_f32_16x16x32_bf16 v[172:175], v[148:151], v[160:163], v[176:179]
	v_mfma_f32_16x16x32_bf16 v[176:179], v[140:143], v[192:195], v[180:183]
	v_mfma_f32_16x16x32_bf16 v[140:143], v[144:147], v[204:207], v[30:33]
	v_mfma_f32_16x16x32_bf16 v[30:33], v[148:151], v[200:203], v[34:37]
	v_mfma_f32_16x16x32_bf16 v[22:25], v[144:147], v[126:129], v[22:25]
	v_mfma_f32_16x16x32_bf16 v[180:183], v[148:151], v[192:195], v[184:187]
	v_mfma_f32_16x16x32_bf16 v[34:37], v[152:155], v[204:207], v[30:33]
	v_mfma_f32_16x16x32_bf16 v[164:167], v[152:155], v[126:129], v[164:167]
	v_mfma_f32_16x16x32_bf16 v[168:171], v[144:147], v[188:191], v[168:171]
	v_mfma_f32_16x16x32_bf16 v[172:175], v[152:155], v[188:191], v[172:175]
	v_mfma_f32_16x16x32_bf16 v[176:179], v[144:147], v[196:199], v[176:179]
	v_mfma_f32_16x16x32_bf16 v[180:183], v[152:155], v[196:199], v[180:183]
	s_setprio 0
	s_barrier
	s_mov_b32 m0, s8
	s_nop 0
	global_load_lds_dwordx4 v[18:19], off
	s_mov_b32 m0, s7
	s_nop 0
	global_load_lds_dwordx4 v[20:21], off
	s_waitcnt vmcnt(6)
	s_barrier
	s_setprio 1
	v_mfma_f32_16x16x32_bf16 v[30:33], v[220:223], v[70:73], v[42:45]
	v_mfma_f32_16x16x32_bf16 v[18:21], v[106:109], v[70:73], v[38:41]
	v_mfma_f32_16x16x32_bf16 v[38:41], v[224:227], v[126:129], v[30:33]
	v_mfma_f32_16x16x32_bf16 v[30:33], v[106:109], v[160:163], v[74:77]
	v_mfma_f32_16x16x32_bf16 v[144:147], v[216:219], v[188:191], v[30:33]
	v_mfma_f32_16x16x32_bf16 v[30:33], v[220:223], v[160:163], v[118:121]
	v_mfma_f32_16x16x32_bf16 v[148:151], v[224:227], v[188:191], v[30:33]
	v_mfma_f32_16x16x32_bf16 v[30:33], v[106:109], v[192:195], v[122:125]
	v_mfma_f32_16x16x32_bf16 v[152:155], v[216:219], v[196:199], v[30:33]
	v_mfma_f32_16x16x32_bf16 v[30:33], v[220:223], v[192:195], v[134:137]
	v_mfma_f32_16x16x32_bf16 v[134:137], v[224:227], v[196:199], v[30:33]
	v_mfma_f32_16x16x32_bf16 v[30:33], v[106:109], v[200:203], v[110:113]
	v_mfma_f32_16x16x32_bf16 v[18:21], v[216:219], v[126:129], v[18:21]
	v_mfma_f32_16x16x32_bf16 v[160:163], v[216:219], v[204:207], v[30:33]
	v_mfma_f32_16x16x32_bf16 v[30:33], v[220:223], v[200:203], v[114:117]
	v_mfma_f32_16x16x32_bf16 v[184:187], v[224:227], v[204:207], v[30:33]
	s_setprio 0
	s_barrier
	ds_read_b128 v[188:191], v230
	ds_read_b128 v[192:195], v230 offset:1024
	ds_read_b128 v[196:199], v230 offset:2048
	ds_read_b128 v[200:203], v230 offset:3072
	s_mov_b32 m0, s21
	ds_read_b128 v[30:33], v133 offset:32768
	ds_read_b128 v[42:45], v133 offset:33792
	ds_read_b128 v[70:73], v133 offset:34816
	ds_read_b128 v[204:207], v133 offset:35840
	ds_read_b128 v[208:211], v133 offset:36864
	ds_read_b128 v[216:219], v133 offset:37888
	ds_read_b128 v[220:223], v133 offset:38912
	ds_read_b128 v[224:227], v133 offset:39936
	global_load_lds_dwordx4 v[12:13], off
	s_mov_b32 m0, s22
	s_nop 0
	global_load_lds_dwordx4 v[14:15], off
	s_waitcnt lgkmcnt(8)
	s_barrier
	s_waitcnt lgkmcnt(0)
	s_setprio 1
	s_waitcnt lgkmcnt(0)
	v_mfma_f32_16x16x32_bf16 v[12:15], v[188:191], v[30:33], v[78:81]
	v_mfma_f32_16x16x32_bf16 v[126:129], v[192:195], v[42:45], v[12:15]
	v_mfma_f32_16x16x32_bf16 v[12:15], v[196:199], v[30:33], v[82:85]
	v_mfma_f32_16x16x32_bf16 v[122:125], v[200:203], v[42:45], v[12:15]
	v_mfma_f32_16x16x32_bf16 v[12:15], v[188:191], v[70:73], v[86:89]
	v_mfma_f32_16x16x32_bf16 v[110:113], v[192:195], v[204:207], v[12:15]
	v_mfma_f32_16x16x32_bf16 v[12:15], v[196:199], v[70:73], v[90:93]
	v_mfma_f32_16x16x32_bf16 v[106:109], v[200:203], v[204:207], v[12:15]
	v_mfma_f32_16x16x32_bf16 v[12:15], v[188:191], v[208:211], v[94:97]
	v_mfma_f32_16x16x32_bf16 v[94:97], v[192:195], v[216:219], v[12:15]
	v_mfma_f32_16x16x32_bf16 v[12:15], v[196:199], v[208:211], v[98:101]
	v_mfma_f32_16x16x32_bf16 v[90:93], v[200:203], v[216:219], v[12:15]
	v_mfma_f32_16x16x32_bf16 v[12:15], v[188:191], v[220:223], v[102:105]
	v_mfma_f32_16x16x32_bf16 v[78:81], v[192:195], v[224:227], v[12:15]
	v_mfma_f32_16x16x32_bf16 v[12:15], v[196:199], v[220:223], v[212:215]
	v_mfma_f32_16x16x32_bf16 v[74:77], v[200:203], v[224:227], v[12:15]
	s_setprio 0
	s_barrier
	s_mov_b32 m0, s20
	ds_read_b128 v[212:215], v236
	ds_read_b128 v[228:231], v236 offset:1024
	ds_read_b128 v[232:235], v236 offset:2048
	ds_read_b128 v[236:239], v236 offset:3072
	global_load_lds_dwordx4 v[10:11], off
	s_mov_b32 m0, s23
	s_nop 0
	global_load_lds_dwordx4 v[16:17], off
	s_barrier
	s_waitcnt lgkmcnt(0)
	s_setprio 1
	s_waitcnt lgkmcnt(0)
	v_mfma_f32_16x16x32_bf16 v[10:13], v[212:215], v[30:33], v[26:29]
	v_mfma_f32_16x16x32_bf16 v[118:121], v[228:231], v[42:45], v[10:13]
	v_mfma_f32_16x16x32_bf16 v[10:13], v[232:235], v[30:33], v[46:49]
	v_mfma_f32_16x16x32_bf16 v[114:117], v[236:239], v[42:45], v[10:13]
	v_mfma_f32_16x16x32_bf16 v[10:13], v[212:215], v[70:73], v[50:53]
	v_mfma_f32_16x16x32_bf16 v[102:105], v[228:231], v[204:207], v[10:13]
	v_mfma_f32_16x16x32_bf16 v[10:13], v[232:235], v[70:73], v[54:57]
	v_mfma_f32_16x16x32_bf16 v[98:101], v[236:239], v[204:207], v[10:13]
	v_mfma_f32_16x16x32_bf16 v[10:13], v[212:215], v[208:211], v[58:61]
	v_mfma_f32_16x16x32_bf16 v[86:89], v[228:231], v[216:219], v[10:13]
	v_mfma_f32_16x16x32_bf16 v[10:13], v[232:235], v[208:211], v[62:65]
	v_mfma_f32_16x16x32_bf16 v[82:85], v[236:239], v[216:219], v[10:13]
	v_mfma_f32_16x16x32_bf16 v[10:13], v[212:215], v[220:223], v[66:69]
	v_mfma_f32_16x16x32_bf16 v[70:73], v[228:231], v[224:227], v[10:13]
	v_mfma_f32_16x16x32_bf16 v[10:13], v[232:235], v[220:223], v[156:159]
	v_mfma_f32_16x16x32_bf16 v[66:69], v[236:239], v[224:227], v[10:13]
	s_setprio 0
	s_mov_b32 m0, s18
	s_barrier
	ds_read_b128 v[50:53], v133 offset:49152
	ds_read_b128 v[156:159], v133 offset:50176
	ds_read_b128 v[204:207], v133 offset:51200
	ds_read_b128 v[208:211], v133 offset:52224
	ds_read_b128 v[216:219], v133 offset:53248
	ds_read_b128 v[220:223], v133 offset:54272
	ds_read_b128 v[224:227], v133 offset:55296
	ds_read_b128 v[240:243], v133 offset:56320
	global_load_lds_dwordx4 v[6:7], off
	s_mov_b32 m0, s19
	s_nop 0
	global_load_lds_dwordx4 v[8:9], off
	s_barrier
	s_waitcnt lgkmcnt(0)
	s_setprio 1
	s_waitcnt lgkmcnt(0)
	v_mfma_f32_16x16x32_bf16 v[6:9], v[188:191], v[50:53], v[22:25]
	v_mfma_f32_16x16x32_bf16 v[62:65], v[192:195], v[156:159], v[6:9]
	v_mfma_f32_16x16x32_bf16 v[6:9], v[196:199], v[50:53], v[164:167]
	v_mfma_f32_16x16x32_bf16 v[58:61], v[200:203], v[156:159], v[6:9]
	v_mfma_f32_16x16x32_bf16 v[6:9], v[188:191], v[204:207], v[168:171]
	v_mfma_f32_16x16x32_bf16 v[46:49], v[192:195], v[208:211], v[6:9]
	v_mfma_f32_16x16x32_bf16 v[6:9], v[196:199], v[204:207], v[172:175]
	v_mfma_f32_16x16x32_bf16 v[42:45], v[200:203], v[208:211], v[6:9]
	v_mfma_f32_16x16x32_bf16 v[6:9], v[188:191], v[216:219], v[176:179]
	v_mfma_f32_16x16x32_bf16 v[30:33], v[192:195], v[220:223], v[6:9]
	v_mfma_f32_16x16x32_bf16 v[6:9], v[196:199], v[216:219], v[180:183]
	v_mfma_f32_16x16x32_bf16 v[26:29], v[200:203], v[220:223], v[6:9]
	v_mfma_f32_16x16x32_bf16 v[6:9], v[188:191], v[224:227], v[140:143]
	v_mfma_f32_16x16x32_bf16 v[14:17], v[192:195], v[240:243], v[6:9]
	v_mfma_f32_16x16x32_bf16 v[6:9], v[196:199], v[224:227], v[34:37]
	v_mfma_f32_16x16x32_bf16 v[10:13], v[200:203], v[240:243], v[6:9]
	s_setprio 0
	s_barrier
	s_mov_b32 m0, s16
	s_nop 0
	global_load_lds_dwordx4 v[2:3], off
	s_mov_b32 m0, s17
	s_nop 0
	global_load_lds_dwordx4 v[4:5], off
	s_waitcnt vmcnt(6)
	s_barrier
	s_setprio 1
	v_mfma_f32_16x16x32_bf16 v[2:5], v[212:215], v[50:53], v[18:21]
	v_mfma_f32_16x16x32_bf16 v[54:57], v[228:231], v[156:159], v[2:5]
	v_mfma_f32_16x16x32_bf16 v[2:5], v[232:235], v[50:53], v[38:41]
	v_mfma_f32_16x16x32_bf16 v[50:53], v[236:239], v[156:159], v[2:5]
	v_mfma_f32_16x16x32_bf16 v[2:5], v[212:215], v[204:207], v[144:147]
	v_mfma_f32_16x16x32_bf16 v[38:41], v[228:231], v[208:211], v[2:5]
	v_mfma_f32_16x16x32_bf16 v[2:5], v[232:235], v[204:207], v[148:151]
	v_mfma_f32_16x16x32_bf16 v[34:37], v[236:239], v[208:211], v[2:5]
	v_mfma_f32_16x16x32_bf16 v[2:5], v[212:215], v[216:219], v[152:155]
	v_mfma_f32_16x16x32_bf16 v[22:25], v[228:231], v[220:223], v[2:5]
	v_mfma_f32_16x16x32_bf16 v[2:5], v[232:235], v[216:219], v[134:137]
	v_mfma_f32_16x16x32_bf16 v[18:21], v[236:239], v[220:223], v[2:5]
	v_mfma_f32_16x16x32_bf16 v[2:5], v[212:215], v[224:227], v[160:163]
	v_mfma_f32_16x16x32_bf16 v[6:9], v[228:231], v[240:243], v[2:5]
	v_mfma_f32_16x16x32_bf16 v[2:5], v[232:235], v[224:227], v[184:187]
	v_mfma_f32_16x16x32_bf16 v[2:5], v[236:239], v[240:243], v[2:5]
	s_setprio 0
	s_barrier
	s_cbranch_scc1 .LBB0_804
	s_barrier

.LBB0_947:
	s_add_u32 s64, s18, s52
	s_addc_u32 s65, s19, s53
	s_add_u32 s66, s18, s62
	s_addc_u32 s67, s19, s63
	s_add_i32 s30, 0, 0x18000
	s_mov_b64 s[52:53], 0x80
	s_add_i32 s29, s30, s0
	v_lshl_add_u64 v[8:9], v[4:5], 0, s[52:53]
	s_mov_b32 m0, s29
	s_mov_b64 s[54:55], 0x8080
	s_add_i32 s33, s29, 0x2000
	global_load_lds_dwordx4 v[8:9], off
	v_lshl_add_u64 v[8:9], v[4:5], 0, s[54:55]
	s_mov_b32 m0, s33
	s_add_i32 s38, s25, 0x8000
	global_load_lds_dwordx4 v[8:9], off
	v_lshl_add_u64 v[8:9], v[2:3], 0, s[52:53]
	s_mov_b32 m0, s38
	s_mov_b64 s[56:57], 0x20080
	s_add_i32 s39, s25, 0xa000
	s_add_i32 s31, 0, 0x1c000
	global_load_lds_dwordx4 v[8:9], off
	v_lshl_add_u64 v[8:9], v[2:3], 0, s[56:57]
	s_mov_b32 m0, s39
	s_mov_b64 s[58:59], 0x10080
	s_add_i32 s70, s31, s0
	global_load_lds_dwordx4 v[8:9], off
	v_lshl_add_u64 v[8:9], v[4:5], 0, s[58:59]
	s_mov_b32 m0, s70
	s_mov_b64 s[60:61], 0x18080
	s_add_i32 s71, s70, 0x2000
	global_load_lds_dwordx4 v[8:9], off
	v_lshl_add_u64 v[8:9], v[4:5], 0, s[60:61]
	s_mov_b32 m0, s71
	v_bfe_u32 v237, v6, 4, 2
	global_load_lds_dwordx4 v[8:9], off
	s_waitcnt vmcnt(10)
	s_barrier
	v_and_b32_e32 v234, 15, v6
	v_lshlrev_b32_e32 v7, 4, v237
	v_lshlrev_b32_e32 v6, 2, v6
	s_and_b32 s6, s1, 3
	v_lshl_or_b32 v7, v234, 6, v7
	s_lshl_b32 s1, s5, 13
	v_and_b32_e32 v6, 32, v6
	v_bitop3_b32 v8, v7, s1, v6 bitop3:0xde
	s_lshl_b32 s1, s6, 12
	v_bitop3_b32 v22, v7, s1, v6 bitop3:0xde
	s_add_i32 s75, 0, 0x10000
	v_add_u32_e32 v136, s75, v22
	s_waitcnt vmcnt(6)
	s_barrier
	v_add_u32_e32 v137, 0, v8
	ds_read_b128 v[6:9], v136
	ds_read_b128 v[10:13], v136 offset:1024
	ds_read_b128 v[14:17], v136 offset:2048
	ds_read_b128 v[18:21], v136 offset:3072
	s_add_i32 s77, 0, 0x14000
	s_lshl_b32 s35, s5, 6
	s_mov_b32 s72, 2
	v_add_u32_e32 v138, s77, v22
	v_add_u32_e32 v139, s30, v22
	v_add_u32_e32 v140, s31, v22
	s_mov_b64 s[30:31], 0x40080
	s_add_i32 s73, s25, 0xc000
	v_lshl_add_u64 v[54:55], v[2:3], 0, s[30:31]
	s_mov_b32 m0, s73
	s_mov_b64 s[30:31], 0x60080
	s_add_i32 s74, s25, 0xe000
	ds_read_b128 v[22:25], v137
	ds_read_b128 v[26:29], v137 offset:1024
	ds_read_b128 v[30:33], v137 offset:2048
	ds_read_b128 v[34:37], v137 offset:3072
	ds_read_b128 v[38:41], v137 offset:4096
	ds_read_b128 v[42:45], v137 offset:5120
	ds_read_b128 v[46:49], v137 offset:6144
	ds_read_b128 v[50:53], v137 offset:7168
	global_load_lds_dwordx4 v[54:55], off
	v_lshl_add_u64 v[54:55], v[2:3], 0, s[30:31]
	s_mov_b32 m0, s74
	s_nop 0
	global_load_lds_dwordx4 v[54:55], off
	s_waitcnt lgkmcnt(8)
	s_barrier
	s_waitcnt lgkmcnt(0)
	s_setprio 1
	s_waitcnt lgkmcnt(0)
	v_mfma_f32_16x16x32_bf16 v[54:57], v[6:9], v[22:25], 0
	v_mfma_f32_16x16x32_bf16 v[58:61], v[14:17], v[22:25], 0
	v_mfma_f32_16x16x32_bf16 v[62:65], v[6:9], v[30:33], 0
	v_mfma_f32_16x16x32_bf16 v[66:69], v[14:17], v[30:33], 0
	v_mfma_f32_16x16x32_bf16 v[70:73], v[6:9], v[38:41], 0
	v_mfma_f32_16x16x32_bf16 v[74:77], v[14:17], v[38:41], 0
	v_mfma_f32_16x16x32_bf16 v[78:81], v[6:9], v[46:49], 0
	v_mfma_f32_16x16x32_bf16 v[82:85], v[14:17], v[46:49], 0
	v_mfma_f32_16x16x32_bf16 v[54:57], v[10:13], v[26:29], v[54:57]
	v_mfma_f32_16x16x32_bf16 v[58:61], v[18:21], v[26:29], v[58:61]
	v_mfma_f32_16x16x32_bf16 v[62:65], v[10:13], v[34:37], v[62:65]
	v_mfma_f32_16x16x32_bf16 v[66:69], v[18:21], v[34:37], v[66:69]
	v_mfma_f32_16x16x32_bf16 v[70:73], v[10:13], v[42:45], v[70:73]
	v_mfma_f32_16x16x32_bf16 v[74:77], v[18:21], v[42:45], v[74:77]
	v_mfma_f32_16x16x32_bf16 v[78:81], v[10:13], v[50:53], v[78:81]
	v_mfma_f32_16x16x32_bf16 v[82:85], v[18:21], v[50:53], v[82:85]
	s_setprio 0
	s_barrier
	s_mov_b64 s[30:31], 0x100
	s_add_i32 s75, s75, s0
	v_lshl_add_u64 v[102:103], v[4:5], 0, s[30:31]
	s_mov_b32 m0, s75
	s_mov_b64 s[68:69], 0x8100
	s_add_i32 s76, s75, 0x2000
	ds_read_b128 v[86:89], v138
	ds_read_b128 v[90:93], v138 offset:1024
	ds_read_b128 v[94:97], v138 offset:2048
	ds_read_b128 v[98:101], v138 offset:3072
	global_load_lds_dwordx4 v[102:103], off
	v_lshl_add_u64 v[102:103], v[4:5], 0, s[68:69]
	s_mov_b32 m0, s76
	s_nop 0
	global_load_lds_dwordx4 v[102:103], off
	s_barrier
	s_waitcnt lgkmcnt(0)
	s_setprio 1
	s_waitcnt lgkmcnt(0)
	v_mfma_f32_16x16x32_bf16 v[102:105], v[86:89], v[22:25], 0
	v_mfma_f32_16x16x32_bf16 v[22:25], v[94:97], v[22:25], 0
	v_mfma_f32_16x16x32_bf16 v[102:105], v[90:93], v[26:29], v[102:105]
	v_mfma_f32_16x16x32_bf16 v[22:25], v[98:101], v[26:29], v[22:25]
	v_mfma_f32_16x16x32_bf16 v[26:29], v[86:89], v[30:33], 0
	v_mfma_f32_16x16x32_bf16 v[30:33], v[94:97], v[30:33], 0
	v_mfma_f32_16x16x32_bf16 v[26:29], v[90:93], v[34:37], v[26:29]
	v_mfma_f32_16x16x32_bf16 v[30:33], v[98:101], v[34:37], v[30:33]
	v_mfma_f32_16x16x32_bf16 v[34:37], v[86:89], v[38:41], 0
	v_mfma_f32_16x16x32_bf16 v[38:41], v[94:97], v[38:41], 0
	v_mfma_f32_16x16x32_bf16 v[34:37], v[90:93], v[42:45], v[34:37]
	v_mfma_f32_16x16x32_bf16 v[38:41], v[98:101], v[42:45], v[38:41]
	v_mfma_f32_16x16x32_bf16 v[42:45], v[86:89], v[46:49], 0
	v_mfma_f32_16x16x32_bf16 v[46:49], v[94:97], v[46:49], 0
	v_mfma_f32_16x16x32_bf16 v[42:45], v[90:93], v[50:53], v[42:45]
	v_mfma_f32_16x16x32_bf16 v[46:49], v[98:101], v[50:53], v[46:49]
	s_setprio 0
	s_mov_b32 m0, s25
	v_lshl_add_u64 v[146:147], v[2:3], 0, s[30:31]
	s_mov_b64 s[30:31], 0x20100
	s_barrier
	ds_read_b128 v[50:53], v137 offset:16384
	ds_read_b128 v[106:109], v137 offset:17408
	ds_read_b128 v[110:113], v137 offset:18432
	ds_read_b128 v[118:121], v137 offset:19456
	ds_read_b128 v[122:125], v137 offset:20480
	ds_read_b128 v[126:129], v137 offset:21504
	ds_read_b128 v[130:133], v137 offset:22528
	ds_read_b128 v[142:145], v137 offset:23552
	global_load_lds_dwordx4 v[146:147], off
	v_lshl_add_u64 v[146:147], v[2:3], 0, s[30:31]
	s_mov_b32 m0, s26
	s_nop 0
	global_load_lds_dwordx4 v[146:147], off
	s_barrier
	s_waitcnt lgkmcnt(0)
	s_setprio 1
	s_waitcnt lgkmcnt(0)
	v_mfma_f32_16x16x32_bf16 v[146:149], v[6:9], v[50:53], 0
	v_mfma_f32_16x16x32_bf16 v[154:157], v[6:9], v[110:113], 0
	v_mfma_f32_16x16x32_bf16 v[162:165], v[6:9], v[122:125], 0
	v_mfma_f32_16x16x32_bf16 v[6:9], v[6:9], v[130:133], 0
	v_mfma_f32_16x16x32_bf16 v[146:149], v[10:13], v[106:109], v[146:149]
	v_mfma_f32_16x16x32_bf16 v[154:157], v[10:13], v[118:121], v[154:157]
	v_mfma_f32_16x16x32_bf16 v[162:165], v[10:13], v[126:129], v[162:165]
	v_mfma_f32_16x16x32_bf16 v[6:9], v[10:13], v[142:145], v[6:9]
	v_mfma_f32_16x16x32_bf16 v[10:13], v[14:17], v[130:133], 0
	v_mfma_f32_16x16x32_bf16 v[150:153], v[14:17], v[50:53], 0
	v_mfma_f32_16x16x32_bf16 v[158:161], v[14:17], v[110:113], 0
	v_mfma_f32_16x16x32_bf16 v[166:169], v[14:17], v[122:125], 0
	v_mfma_f32_16x16x32_bf16 v[10:13], v[18:21], v[142:145], v[10:13]
	v_mfma_f32_16x16x32_bf16 v[150:153], v[18:21], v[106:109], v[150:153]
	v_mfma_f32_16x16x32_bf16 v[158:161], v[18:21], v[118:121], v[158:161]
	v_mfma_f32_16x16x32_bf16 v[166:169], v[18:21], v[126:129], v[166:169]
	s_setprio 0
	s_barrier
	s_mov_b64 s[30:31], 0x10100
	s_add_i32 s77, s77, s0
	v_lshl_add_u64 v[14:15], v[4:5], 0, s[30:31]
	s_mov_b32 m0, s77
	s_mov_b64 s[0:1], 0x18100
	s_add_i32 s78, s77, 0x2000
	global_load_lds_dwordx4 v[14:15], off
	v_lshl_add_u64 v[14:15], v[4:5], 0, s[0:1]
	s_mov_b32 m0, s78
	s_nop 0
	global_load_lds_dwordx4 v[14:15], off
	s_waitcnt vmcnt(6)
	s_barrier
	s_setprio 1
	v_mfma_f32_16x16x32_bf16 v[14:17], v[86:89], v[50:53], 0
	v_mfma_f32_16x16x32_bf16 v[18:21], v[94:97], v[50:53], 0
	v_mfma_f32_16x16x32_bf16 v[14:17], v[90:93], v[106:109], v[14:17]
	v_mfma_f32_16x16x32_bf16 v[18:21], v[98:101], v[106:109], v[18:21]
	v_mfma_f32_16x16x32_bf16 v[50:53], v[86:89], v[110:113], 0
	v_mfma_f32_16x16x32_bf16 v[106:109], v[94:97], v[110:113], 0
	v_mfma_f32_16x16x32_bf16 v[110:113], v[86:89], v[122:125], 0
	v_mfma_f32_16x16x32_bf16 v[86:89], v[86:89], v[130:133], 0
	v_mfma_f32_16x16x32_bf16 v[50:53], v[90:93], v[118:121], v[50:53]
	v_mfma_f32_16x16x32_bf16 v[106:109], v[98:101], v[118:121], v[106:109]
	v_mfma_f32_16x16x32_bf16 v[110:113], v[90:93], v[126:129], v[110:113]
	v_mfma_f32_16x16x32_bf16 v[118:121], v[94:97], v[122:125], 0
	v_mfma_f32_16x16x32_bf16 v[86:89], v[90:93], v[142:145], v[86:89]
	v_mfma_f32_16x16x32_bf16 v[90:93], v[94:97], v[130:133], 0
	v_mfma_f32_16x16x32_bf16 v[118:121], v[98:101], v[126:129], v[118:121]
	v_mfma_f32_16x16x32_bf16 v[90:93], v[98:101], v[142:145], v[90:93]
	s_setprio 0
	s_barrier
	ds_read_b128 v[94:97], v139
	ds_read_b128 v[98:101], v139 offset:1024
	ds_read_b128 v[122:125], v139 offset:2048
	ds_read_b128 v[126:129], v139 offset:3072
	s_mov_b64 s[0:1], 0x40100
	s_mov_b32 m0, s27
	v_lshl_add_u64 v[194:195], v[2:3], 0, s[0:1]
	s_mov_b64 s[0:1], 0x60100
	ds_read_b128 v[130:133], v137 offset:32768
	ds_read_b128 v[142:145], v137 offset:33792
	ds_read_b128 v[170:173], v137 offset:34816
	ds_read_b128 v[174:177], v137 offset:35840
	ds_read_b128 v[178:181], v137 offset:36864
	ds_read_b128 v[182:185], v137 offset:37888
	ds_read_b128 v[186:189], v137 offset:38912
	ds_read_b128 v[190:193], v137 offset:39936
	global_load_lds_dwordx4 v[194:195], off
	v_lshl_add_u64 v[194:195], v[2:3], 0, s[0:1]
	s_mov_b32 m0, s28
	s_nop 0
	global_load_lds_dwordx4 v[194:195], off
	s_waitcnt lgkmcnt(8)
	s_barrier
	s_waitcnt lgkmcnt(0)
	s_setprio 1
	s_waitcnt lgkmcnt(0)
	v_mfma_f32_16x16x32_bf16 v[54:57], v[94:97], v[130:133], v[54:57]
	v_mfma_f32_16x16x32_bf16 v[58:61], v[122:125], v[130:133], v[58:61]
	v_mfma_f32_16x16x32_bf16 v[62:65], v[94:97], v[170:173], v[62:65]
	v_mfma_f32_16x16x32_bf16 v[66:69], v[122:125], v[170:173], v[66:69]
	v_mfma_f32_16x16x32_bf16 v[70:73], v[94:97], v[178:181], v[70:73]
	v_mfma_f32_16x16x32_bf16 v[74:77], v[122:125], v[178:181], v[74:77]
	v_mfma_f32_16x16x32_bf16 v[78:81], v[94:97], v[186:189], v[78:81]
	v_mfma_f32_16x16x32_bf16 v[82:85], v[122:125], v[186:189], v[82:85]
	v_mfma_f32_16x16x32_bf16 v[54:57], v[98:101], v[142:145], v[54:57]
	v_mfma_f32_16x16x32_bf16 v[58:61], v[126:129], v[142:145], v[58:61]
	v_mfma_f32_16x16x32_bf16 v[62:65], v[98:101], v[174:177], v[62:65]
	v_mfma_f32_16x16x32_bf16 v[66:69], v[126:129], v[174:177], v[66:69]
	v_mfma_f32_16x16x32_bf16 v[70:73], v[98:101], v[182:185], v[70:73]
	v_mfma_f32_16x16x32_bf16 v[74:77], v[126:129], v[182:185], v[74:77]
	v_mfma_f32_16x16x32_bf16 v[78:81], v[98:101], v[190:193], v[78:81]
	v_mfma_f32_16x16x32_bf16 v[82:85], v[126:129], v[190:193], v[82:85]
	s_setprio 0
	s_barrier
	s_mov_b64 s[0:1], 0x180
	s_mov_b32 m0, s29
	v_lshl_add_u64 v[210:211], v[4:5], 0, s[0:1]
	s_mov_b64 s[30:31], 0x8180
	ds_read_b128 v[194:197], v140
	ds_read_b128 v[198:201], v140 offset:1024
	ds_read_b128 v[202:205], v140 offset:2048
	ds_read_b128 v[206:209], v140 offset:3072
	global_load_lds_dwordx4 v[210:211], off
	v_lshl_add_u64 v[210:211], v[4:5], 0, s[30:31]
	s_mov_b32 m0, s33
	s_nop 0
	global_load_lds_dwordx4 v[210:211], off
	s_barrier
	s_waitcnt lgkmcnt(0)
	s_setprio 1
	s_waitcnt lgkmcnt(0)
	v_mfma_f32_16x16x32_bf16 v[102:105], v[194:197], v[130:133], v[102:105]
	v_mfma_f32_16x16x32_bf16 v[22:25], v[202:205], v[130:133], v[22:25]
	v_mfma_f32_16x16x32_bf16 v[26:29], v[194:197], v[170:173], v[26:29]
	v_mfma_f32_16x16x32_bf16 v[30:33], v[202:205], v[170:173], v[30:33]
	v_mfma_f32_16x16x32_bf16 v[34:37], v[194:197], v[178:181], v[34:37]
	v_mfma_f32_16x16x32_bf16 v[38:41], v[202:205], v[178:181], v[38:41]
	v_mfma_f32_16x16x32_bf16 v[42:45], v[194:197], v[186:189], v[42:45]
	v_mfma_f32_16x16x32_bf16 v[46:49], v[202:205], v[186:189], v[46:49]
	v_mfma_f32_16x16x32_bf16 v[102:105], v[198:201], v[142:145], v[102:105]
	v_mfma_f32_16x16x32_bf16 v[22:25], v[206:209], v[142:145], v[22:25]
	v_mfma_f32_16x16x32_bf16 v[26:29], v[198:201], v[174:177], v[26:29]
	v_mfma_f32_16x16x32_bf16 v[30:33], v[206:209], v[174:177], v[30:33]
	v_mfma_f32_16x16x32_bf16 v[34:37], v[198:201], v[182:185], v[34:37]
	v_mfma_f32_16x16x32_bf16 v[38:41], v[206:209], v[182:185], v[38:41]
	v_mfma_f32_16x16x32_bf16 v[42:45], v[198:201], v[190:193], v[42:45]
	v_mfma_f32_16x16x32_bf16 v[46:49], v[206:209], v[190:193], v[46:49]
	s_setprio 0
	s_mov_b32 m0, s38
	v_lshl_add_u64 v[210:211], v[2:3], 0, s[0:1]
	s_mov_b64 s[0:1], 0x20180
	s_barrier
	ds_read_b128 v[130:133], v137 offset:49152
	ds_read_b128 v[142:145], v137 offset:50176
	ds_read_b128 v[170:173], v137 offset:51200
	ds_read_b128 v[174:177], v137 offset:52224
	ds_read_b128 v[178:181], v137 offset:53248
	ds_read_b128 v[182:185], v137 offset:54272
	ds_read_b128 v[186:189], v137 offset:55296
	ds_read_b128 v[190:193], v137 offset:56320
	global_load_lds_dwordx4 v[210:211], off
	v_lshl_add_u64 v[210:211], v[2:3], 0, s[0:1]
	s_mov_b32 m0, s39
	s_nop 0
	global_load_lds_dwordx4 v[210:211], off
	s_barrier
	s_waitcnt lgkmcnt(0)
	s_setprio 1
	s_waitcnt lgkmcnt(0)
	v_mfma_f32_16x16x32_bf16 v[6:9], v[94:97], v[186:189], v[6:9]
	v_mfma_f32_16x16x32_bf16 v[10:13], v[122:125], v[186:189], v[10:13]
	v_mfma_f32_16x16x32_bf16 v[146:149], v[94:97], v[130:133], v[146:149]
	v_mfma_f32_16x16x32_bf16 v[150:153], v[122:125], v[130:133], v[150:153]
	v_mfma_f32_16x16x32_bf16 v[154:157], v[94:97], v[170:173], v[154:157]
	v_mfma_f32_16x16x32_bf16 v[158:161], v[122:125], v[170:173], v[158:161]
	v_mfma_f32_16x16x32_bf16 v[162:165], v[94:97], v[178:181], v[162:165]
	v_mfma_f32_16x16x32_bf16 v[166:169], v[122:125], v[178:181], v[166:169]
	v_mfma_f32_16x16x32_bf16 v[6:9], v[98:101], v[190:193], v[6:9]
	v_mfma_f32_16x16x32_bf16 v[10:13], v[126:129], v[190:193], v[10:13]
	v_mfma_f32_16x16x32_bf16 v[146:149], v[98:101], v[142:145], v[146:149]
	v_mfma_f32_16x16x32_bf16 v[150:153], v[126:129], v[142:145], v[150:153]
	v_mfma_f32_16x16x32_bf16 v[154:157], v[98:101], v[174:177], v[154:157]
	v_mfma_f32_16x16x32_bf16 v[158:161], v[126:129], v[174:177], v[158:161]
	v_mfma_f32_16x16x32_bf16 v[162:165], v[98:101], v[182:185], v[162:165]
	v_mfma_f32_16x16x32_bf16 v[166:169], v[126:129], v[182:185], v[166:169]
	s_setprio 0
	s_barrier
	s_mov_b64 s[0:1], 0x10180
	s_mov_b32 m0, s70
	v_lshl_add_u64 v[94:95], v[4:5], 0, s[0:1]
	s_mov_b64 s[0:1], 0x18180
	global_load_lds_dwordx4 v[94:95], off
	v_lshl_add_u64 v[4:5], v[4:5], 0, s[0:1]
	s_mov_b32 m0, s71
	s_nop 0
	global_load_lds_dwordx4 v[4:5], off
	s_waitcnt vmcnt(6)
	s_barrier
	s_setprio 1
	v_mfma_f32_16x16x32_bf16 v[14:17], v[194:197], v[130:133], v[14:17]
	v_mfma_f32_16x16x32_bf16 v[18:21], v[202:205], v[130:133], v[18:21]
	v_mfma_f32_16x16x32_bf16 v[50:53], v[194:197], v[170:173], v[50:53]
	v_mfma_f32_16x16x32_bf16 v[94:97], v[202:205], v[170:173], v[106:109]
	v_mfma_f32_16x16x32_bf16 v[98:101], v[194:197], v[178:181], v[110:113]
	v_mfma_f32_16x16x32_bf16 v[106:109], v[202:205], v[178:181], v[118:121]
	v_mfma_f32_16x16x32_bf16 v[86:89], v[194:197], v[186:189], v[86:89]
	v_mfma_f32_16x16x32_bf16 v[90:93], v[202:205], v[186:189], v[90:93]
	v_mfma_f32_16x16x32_bf16 v[14:17], v[198:201], v[142:145], v[14:17]
	v_mfma_f32_16x16x32_bf16 v[18:21], v[206:209], v[142:145], v[18:21]
	v_mfma_f32_16x16x32_bf16 v[50:53], v[198:201], v[174:177], v[50:53]
	v_mfma_f32_16x16x32_bf16 v[94:97], v[206:209], v[174:177], v[94:97]
	v_mfma_f32_16x16x32_bf16 v[98:101], v[198:201], v[182:185], v[98:101]
	v_mfma_f32_16x16x32_bf16 v[106:109], v[206:209], v[182:185], v[106:109]
	v_mfma_f32_16x16x32_bf16 v[86:89], v[198:201], v[190:193], v[86:89]
	v_mfma_f32_16x16x32_bf16 v[90:93], v[206:209], v[190:193], v[90:93]
	s_setprio 0
	s_barrier
	ds_read_b128 v[110:113], v136
	ds_read_b128 v[118:121], v136 offset:1024
	ds_read_b128 v[122:125], v136 offset:2048
	ds_read_b128 v[126:129], v136 offset:3072
	s_mov_b64 s[0:1], 0x40180
	s_mov_b32 m0, s73
	v_lshl_add_u64 v[4:5], v[2:3], 0, s[0:1]
	s_mov_b64 s[0:1], 0x60180
	ds_read_b128 v[130:133], v137
	ds_read_b128 v[142:145], v137 offset:1024
	ds_read_b128 v[170:173], v137 offset:2048
	ds_read_b128 v[174:177], v137 offset:3072
	ds_read_b128 v[178:181], v137 offset:4096
	ds_read_b128 v[182:185], v137 offset:5120
	ds_read_b128 v[186:189], v137 offset:6144
	ds_read_b128 v[190:193], v137 offset:7168
	global_load_lds_dwordx4 v[4:5], off
	v_lshl_add_u64 v[2:3], v[2:3], 0, s[0:1]
	s_mov_b32 m0, s74
	s_nop 0
	global_load_lds_dwordx4 v[2:3], off
	s_waitcnt lgkmcnt(8)
	s_barrier
	s_waitcnt lgkmcnt(0)
	s_setprio 1
	s_waitcnt lgkmcnt(0)
	v_mfma_f32_16x16x32_bf16 v[2:5], v[110:113], v[130:133], v[54:57]
	v_mfma_f32_16x16x32_bf16 v[54:57], v[122:125], v[130:133], v[58:61]
	v_mfma_f32_16x16x32_bf16 v[58:61], v[110:113], v[170:173], v[62:65]
	v_mfma_f32_16x16x32_bf16 v[62:65], v[122:125], v[170:173], v[66:69]
	v_mfma_f32_16x16x32_bf16 v[66:69], v[110:113], v[178:181], v[70:73]
	v_mfma_f32_16x16x32_bf16 v[70:73], v[122:125], v[178:181], v[74:77]
	v_mfma_f32_16x16x32_bf16 v[74:77], v[110:113], v[186:189], v[78:81]
	v_mfma_f32_16x16x32_bf16 v[78:81], v[122:125], v[186:189], v[82:85]
	v_mfma_f32_16x16x32_bf16 v[2:5], v[118:121], v[142:145], v[2:5]
	v_mfma_f32_16x16x32_bf16 v[54:57], v[126:129], v[142:145], v[54:57]
	v_mfma_f32_16x16x32_bf16 v[58:61], v[118:121], v[174:177], v[58:61]
	v_mfma_f32_16x16x32_bf16 v[62:65], v[126:129], v[174:177], v[62:65]
	v_mfma_f32_16x16x32_bf16 v[66:69], v[118:121], v[182:185], v[66:69]
	v_mfma_f32_16x16x32_bf16 v[70:73], v[126:129], v[182:185], v[70:73]
	v_mfma_f32_16x16x32_bf16 v[74:77], v[118:121], v[190:193], v[74:77]
	v_mfma_f32_16x16x32_bf16 v[78:81], v[126:129], v[190:193], v[78:81]
	s_setprio 0
	s_barrier
	v_lshl_add_u64 v[250:251], s[66:67], 0, v[114:115]
	s_mov_b64 s[0:1], 0x4e00000
	s_mov_b32 m0, s75
	v_lshl_add_u64 v[206:207], v[250:251], 0, s[0:1]
	s_mov_b64 s[0:1], 0x4e08000
	ds_read_b128 v[82:85], v138
	ds_read_b128 v[194:197], v138 offset:1024
	ds_read_b128 v[198:201], v138 offset:2048
	ds_read_b128 v[202:205], v138 offset:3072
	global_load_lds_dwordx4 v[206:207], off
	v_lshl_add_u64 v[206:207], v[250:251], 0, s[0:1]
	s_mov_b32 m0, s76
	s_nop 0
	global_load_lds_dwordx4 v[206:207], off
	s_barrier
	s_waitcnt lgkmcnt(0)
	s_setprio 1
	s_waitcnt lgkmcnt(0)
	v_mfma_f32_16x16x32_bf16 v[22:25], v[198:201], v[130:133], v[22:25]
	v_mfma_f32_16x16x32_bf16 v[26:29], v[82:85], v[170:173], v[26:29]
	v_mfma_f32_16x16x32_bf16 v[30:33], v[198:201], v[170:173], v[30:33]
	v_mfma_f32_16x16x32_bf16 v[34:37], v[82:85], v[178:181], v[34:37]
	v_mfma_f32_16x16x32_bf16 v[38:41], v[198:201], v[178:181], v[38:41]
	v_mfma_f32_16x16x32_bf16 v[42:45], v[82:85], v[186:189], v[42:45]
	v_mfma_f32_16x16x32_bf16 v[46:49], v[198:201], v[186:189], v[46:49]
	v_mfma_f32_16x16x32_bf16 v[102:105], v[82:85], v[130:133], v[102:105]
	v_mfma_f32_16x16x32_bf16 v[22:25], v[202:205], v[142:145], v[22:25]
	v_mfma_f32_16x16x32_bf16 v[26:29], v[194:197], v[174:177], v[26:29]
	v_mfma_f32_16x16x32_bf16 v[30:33], v[202:205], v[174:177], v[30:33]
	v_mfma_f32_16x16x32_bf16 v[34:37], v[194:197], v[182:185], v[34:37]
	v_mfma_f32_16x16x32_bf16 v[38:41], v[202:205], v[182:185], v[38:41]
	v_mfma_f32_16x16x32_bf16 v[42:45], v[194:197], v[190:193], v[42:45]
	v_mfma_f32_16x16x32_bf16 v[46:49], v[202:205], v[190:193], v[46:49]
	v_mfma_f32_16x16x32_bf16 v[206:209], v[194:197], v[142:145], v[102:105]
	s_setprio 0
	v_lshl_add_u64 v[252:253], s[64:65], 0, v[116:117]
	s_mov_b64 s[0:1], 0x8e00000
	s_mov_b32 m0, s25
	v_lshl_add_u64 v[190:191], v[252:253], 0, s[0:1]
	s_mov_b64 s[0:1], 0x8e20000
	s_barrier
	ds_read_b128 v[102:105], v137 offset:16384
	ds_read_b128 v[130:133], v137 offset:17408
	ds_read_b128 v[142:145], v137 offset:18432
	ds_read_b128 v[170:173], v137 offset:19456
	ds_read_b128 v[174:177], v137 offset:20480
	ds_read_b128 v[178:181], v137 offset:21504
	ds_read_b128 v[182:185], v137 offset:22528
	ds_read_b128 v[186:189], v137 offset:23552
	global_load_lds_dwordx4 v[190:191], off
	v_lshl_add_u64 v[190:191], v[252:253], 0, s[0:1]
	s_mov_b32 m0, s26
	s_nop 0
	global_load_lds_dwordx4 v[190:191], off
	s_barrier
	s_waitcnt lgkmcnt(0)
	s_setprio 1
	s_waitcnt lgkmcnt(0)
	v_mfma_f32_16x16x32_bf16 v[6:9], v[110:113], v[182:185], v[6:9]
	v_mfma_f32_16x16x32_bf16 v[10:13], v[122:125], v[182:185], v[10:13]
	v_mfma_f32_16x16x32_bf16 v[146:149], v[110:113], v[102:105], v[146:149]
	v_mfma_f32_16x16x32_bf16 v[150:153], v[122:125], v[102:105], v[150:153]
	v_mfma_f32_16x16x32_bf16 v[154:157], v[110:113], v[142:145], v[154:157]
	v_mfma_f32_16x16x32_bf16 v[158:161], v[122:125], v[142:145], v[158:161]
	v_mfma_f32_16x16x32_bf16 v[162:165], v[110:113], v[174:177], v[162:165]
	v_mfma_f32_16x16x32_bf16 v[166:169], v[122:125], v[174:177], v[166:169]
	v_mfma_f32_16x16x32_bf16 v[6:9], v[118:121], v[186:189], v[6:9]
	v_mfma_f32_16x16x32_bf16 v[10:13], v[126:129], v[186:189], v[10:13]
	v_mfma_f32_16x16x32_bf16 v[146:149], v[118:121], v[130:133], v[146:149]
	v_mfma_f32_16x16x32_bf16 v[150:153], v[126:129], v[130:133], v[150:153]
	v_mfma_f32_16x16x32_bf16 v[154:157], v[118:121], v[170:173], v[154:157]
	v_mfma_f32_16x16x32_bf16 v[158:161], v[126:129], v[170:173], v[158:161]
	v_mfma_f32_16x16x32_bf16 v[162:165], v[118:121], v[178:181], v[162:165]
	v_mfma_f32_16x16x32_bf16 v[166:169], v[126:129], v[178:181], v[166:169]
	s_setprio 0
	s_barrier
	s_mov_b64 s[0:1], 0x4e10000
	s_mov_b32 m0, s77
	v_lshl_add_u64 v[110:111], v[250:251], 0, s[0:1]
	s_mov_b64 s[0:1], 0x4e18000
	global_load_lds_dwordx4 v[110:111], off
	v_lshl_add_u64 v[110:111], v[250:251], 0, s[0:1]
	s_mov_b32 m0, s78
	s_nop 0
	global_load_lds_dwordx4 v[110:111], off
	s_waitcnt vmcnt(6)
	s_barrier
	s_setprio 1
	v_mfma_f32_16x16x32_bf16 v[18:21], v[198:201], v[102:105], v[18:21]
	v_mfma_f32_16x16x32_bf16 v[190:193], v[202:205], v[130:133], v[18:21]
	v_mfma_f32_16x16x32_bf16 v[18:21], v[82:85], v[142:145], v[50:53]
	v_mfma_f32_16x16x32_bf16 v[210:213], v[194:197], v[170:173], v[18:21]
	v_mfma_f32_16x16x32_bf16 v[18:21], v[198:201], v[142:145], v[94:97]
	v_mfma_f32_16x16x32_bf16 v[142:145], v[202:205], v[170:173], v[18:21]
	v_mfma_f32_16x16x32_bf16 v[18:21], v[82:85], v[174:177], v[98:101]
	v_mfma_f32_16x16x32_bf16 v[170:173], v[194:197], v[178:181], v[18:21]
	v_mfma_f32_16x16x32_bf16 v[18:21], v[198:201], v[174:177], v[106:109]
	v_mfma_f32_16x16x32_bf16 v[14:17], v[82:85], v[102:105], v[14:17]
	v_mfma_f32_16x16x32_bf16 v[174:177], v[202:205], v[178:181], v[18:21]
	v_mfma_f32_16x16x32_bf16 v[18:21], v[82:85], v[182:185], v[86:89]
	v_mfma_f32_16x16x32_bf16 v[14:17], v[194:197], v[130:133], v[14:17]
	v_mfma_f32_16x16x32_bf16 v[178:181], v[194:197], v[186:189], v[18:21]
	v_mfma_f32_16x16x32_bf16 v[18:21], v[198:201], v[182:185], v[90:93]
	v_mfma_f32_16x16x32_bf16 v[182:185], v[202:205], v[186:189], v[18:21]
	s_setprio 0
	s_barrier
	ds_read_b128 v[186:189], v139
	ds_read_b128 v[194:197], v139 offset:1024
	ds_read_b128 v[198:201], v139 offset:2048
	ds_read_b128 v[202:205], v139 offset:3072
	s_mov_b64 s[0:1], 0x8e40000
	s_mov_b32 m0, s27
	v_lshl_add_u64 v[82:83], v[252:253], 0, s[0:1]
	s_mov_b64 s[0:1], 0x8e60000
	ds_read_b128 v[18:21], v137 offset:32768
	ds_read_b128 v[50:53], v137 offset:33792
	ds_read_b128 v[90:93], v137 offset:34816
	ds_read_b128 v[94:97], v137 offset:35840
	ds_read_b128 v[214:217], v137 offset:36864
	ds_read_b128 v[218:221], v137 offset:37888
	ds_read_b128 v[222:225], v137 offset:38912
	ds_read_b128 v[226:229], v137 offset:39936
	global_load_lds_dwordx4 v[82:83], off
	v_lshl_add_u64 v[82:83], v[252:253], 0, s[0:1]
	s_mov_b32 m0, s28
	s_nop 0
	global_load_lds_dwordx4 v[82:83], off
	s_waitcnt lgkmcnt(8)
	s_barrier
	s_waitcnt lgkmcnt(0)
	s_setprio 1
	s_waitcnt lgkmcnt(0)
	v_mfma_f32_16x16x32_bf16 v[2:5], v[186:189], v[18:21], v[2:5]
	v_mfma_f32_16x16x32_bf16 v[118:121], v[194:197], v[50:53], v[2:5]
	v_mfma_f32_16x16x32_bf16 v[2:5], v[198:201], v[18:21], v[54:57]
	v_mfma_f32_16x16x32_bf16 v[122:125], v[202:205], v[50:53], v[2:5]
	v_mfma_f32_16x16x32_bf16 v[2:5], v[186:189], v[90:93], v[58:61]
	v_mfma_f32_16x16x32_bf16 v[102:105], v[194:197], v[94:97], v[2:5]
	v_mfma_f32_16x16x32_bf16 v[2:5], v[198:201], v[90:93], v[62:65]
	v_mfma_f32_16x16x32_bf16 v[98:101], v[202:205], v[94:97], v[2:5]
	v_mfma_f32_16x16x32_bf16 v[2:5], v[186:189], v[214:217], v[66:69]
	v_mfma_f32_16x16x32_bf16 v[86:89], v[194:197], v[218:221], v[2:5]
	v_mfma_f32_16x16x32_bf16 v[2:5], v[198:201], v[214:217], v[70:73]
	v_mfma_f32_16x16x32_bf16 v[82:85], v[202:205], v[218:221], v[2:5]
	v_mfma_f32_16x16x32_bf16 v[2:5], v[186:189], v[222:225], v[74:77]
	v_mfma_f32_16x16x32_bf16 v[70:73], v[194:197], v[226:229], v[2:5]
	v_mfma_f32_16x16x32_bf16 v[2:5], v[198:201], v[222:225], v[78:81]
	v_mfma_f32_16x16x32_bf16 v[66:69], v[202:205], v[226:229], v[2:5]
	s_setprio 0
	s_barrier
	s_mov_b64 s[0:1], 0x4e00080
	s_mov_b32 m0, s29
	s_nop 2
	v_lshl_add_u64 v[2:3], v[250:251], 0, s[0:1]
	s_mov_b64 s[0:1], 0x4e08080
	ds_read_b128 v[230:233], v140
	ds_read_b128 v[238:241], v140 offset:1024
	ds_read_b128 v[242:245], v140 offset:2048
	ds_read_b128 v[246:249], v140 offset:3072
	global_load_lds_dwordx4 v[2:3], off
	v_lshl_add_u64 v[2:3], v[250:251], 0, s[0:1]
	s_mov_b32 m0, s33
	s_nop 0
	global_load_lds_dwordx4 v[2:3], off
	s_barrier
	s_waitcnt lgkmcnt(0)
	s_setprio 1
	s_waitcnt lgkmcnt(0)
	v_mfma_f32_16x16x32_bf16 v[2:5], v[230:233], v[18:21], v[206:209]
	v_mfma_f32_16x16x32_bf16 v[126:129], v[238:241], v[50:53], v[2:5]
	v_mfma_f32_16x16x32_bf16 v[2:5], v[242:245], v[18:21], v[22:25]
	v_mfma_f32_16x16x32_bf16 v[130:133], v[246:249], v[50:53], v[2:5]
	v_mfma_f32_16x16x32_bf16 v[2:5], v[230:233], v[90:93], v[26:29]
	v_mfma_f32_16x16x32_bf16 v[110:113], v[238:241], v[94:97], v[2:5]
	v_mfma_f32_16x16x32_bf16 v[2:5], v[242:245], v[90:93], v[30:33]
	v_mfma_f32_16x16x32_bf16 v[106:109], v[246:249], v[94:97], v[2:5]
	v_mfma_f32_16x16x32_bf16 v[2:5], v[230:233], v[214:217], v[34:37]
	v_mfma_f32_16x16x32_bf16 v[94:97], v[238:241], v[218:221], v[2:5]
	v_mfma_f32_16x16x32_bf16 v[2:5], v[242:245], v[214:217], v[38:41]
	v_mfma_f32_16x16x32_bf16 v[90:93], v[246:249], v[218:221], v[2:5]
	v_mfma_f32_16x16x32_bf16 v[2:5], v[230:233], v[222:225], v[42:45]
	v_mfma_f32_16x16x32_bf16 v[78:81], v[238:241], v[226:229], v[2:5]
	v_mfma_f32_16x16x32_bf16 v[2:5], v[242:245], v[222:225], v[46:49]
	v_mfma_f32_16x16x32_bf16 v[74:77], v[246:249], v[226:229], v[2:5]
	s_setprio 0
	s_mov_b64 s[0:1], 0x8e00080
	s_mov_b32 m0, s38
	s_nop 3
	v_lshl_add_u64 v[2:3], v[252:253], 0, s[0:1]
	s_mov_b64 s[0:1], 0x8e20080
	s_barrier
	ds_read_b128 v[26:29], v137 offset:49152
	ds_read_b128 v[30:33], v137 offset:50176
	ds_read_b128 v[42:45], v137 offset:51200
	ds_read_b128 v[206:209], v137 offset:52224
	ds_read_b128 v[214:217], v137 offset:53248
	ds_read_b128 v[218:221], v137 offset:54272
	ds_read_b128 v[222:225], v137 offset:55296
	ds_read_b128 v[226:229], v137 offset:56320
	global_load_lds_dwordx4 v[2:3], off
	v_lshl_add_u64 v[2:3], v[252:253], 0, s[0:1]
	s_mov_b32 m0, s39
	s_nop 0
	global_load_lds_dwordx4 v[2:3], off
	s_barrier
	s_waitcnt lgkmcnt(0)
	s_setprio 1
	s_waitcnt lgkmcnt(0)
	v_mfma_f32_16x16x32_bf16 v[2:5], v[186:189], v[26:29], v[146:149]
	v_mfma_f32_16x16x32_bf16 v[54:57], v[194:197], v[30:33], v[2:5]
	v_mfma_f32_16x16x32_bf16 v[2:5], v[198:201], v[26:29], v[150:153]
	v_mfma_f32_16x16x32_bf16 v[50:53], v[202:205], v[30:33], v[2:5]
	v_mfma_f32_16x16x32_bf16 v[2:5], v[186:189], v[42:45], v[154:157]
	v_mfma_f32_16x16x32_bf16 v[38:41], v[194:197], v[206:209], v[2:5]
	v_mfma_f32_16x16x32_bf16 v[2:5], v[198:201], v[42:45], v[158:161]
	v_mfma_f32_16x16x32_bf16 v[34:37], v[202:205], v[206:209], v[2:5]
	v_mfma_f32_16x16x32_bf16 v[2:5], v[186:189], v[214:217], v[162:165]
	v_mfma_f32_16x16x32_bf16 v[22:25], v[194:197], v[218:221], v[2:5]
	v_mfma_f32_16x16x32_bf16 v[2:5], v[198:201], v[214:217], v[166:169]
	v_mfma_f32_16x16x32_bf16 v[18:21], v[202:205], v[218:221], v[2:5]
	v_mfma_f32_16x16x32_bf16 v[2:5], v[186:189], v[222:225], v[6:9]
	v_mfma_f32_16x16x32_bf16 v[6:9], v[194:197], v[226:229], v[2:5]
	v_mfma_f32_16x16x32_bf16 v[2:5], v[198:201], v[222:225], v[10:13]
	v_mfma_f32_16x16x32_bf16 v[2:5], v[202:205], v[226:229], v[2:5]
	s_setprio 0
	s_barrier
	s_mov_b64 s[0:1], 0x4e10080
	s_mov_b32 m0, s70
	v_lshl_add_u64 v[10:11], v[250:251], 0, s[0:1]
	s_mov_b64 s[0:1], 0x4e18080
	global_load_lds_dwordx4 v[10:11], off
	v_lshl_add_u64 v[10:11], v[250:251], 0, s[0:1]
	s_mov_b32 m0, s71
	s_nop 0
	global_load_lds_dwordx4 v[10:11], off
	s_waitcnt vmcnt(6)
	s_barrier
	s_setprio 1
	v_mfma_f32_16x16x32_bf16 v[10:13], v[230:233], v[26:29], v[14:17]
	v_mfma_f32_16x16x32_bf16 v[62:65], v[238:241], v[30:33], v[10:13]
	v_mfma_f32_16x16x32_bf16 v[10:13], v[242:245], v[26:29], v[190:193]
	v_mfma_f32_16x16x32_bf16 v[58:61], v[246:249], v[30:33], v[10:13]
	v_mfma_f32_16x16x32_bf16 v[10:13], v[230:233], v[42:45], v[210:213]
	v_mfma_f32_16x16x32_bf16 v[46:49], v[238:241], v[206:209], v[10:13]
	v_mfma_f32_16x16x32_bf16 v[10:13], v[242:245], v[42:45], v[142:145]
	v_mfma_f32_16x16x32_bf16 v[42:45], v[246:249], v[206:209], v[10:13]
	v_mfma_f32_16x16x32_bf16 v[10:13], v[230:233], v[214:217], v[170:173]
	v_mfma_f32_16x16x32_bf16 v[30:33], v[238:241], v[218:221], v[10:13]
	v_mfma_f32_16x16x32_bf16 v[10:13], v[242:245], v[214:217], v[174:177]
	v_mfma_f32_16x16x32_bf16 v[26:29], v[246:249], v[218:221], v[10:13]
	v_mfma_f32_16x16x32_bf16 v[10:13], v[230:233], v[222:225], v[178:181]
	v_mfma_f32_16x16x32_bf16 v[14:17], v[238:241], v[226:229], v[10:13]
	v_mfma_f32_16x16x32_bf16 v[10:13], v[242:245], v[222:225], v[182:185]
	v_mfma_f32_16x16x32_bf16 v[10:13], v[246:249], v[226:229], v[10:13]
	s_setprio 0
	s_add_i32 s0, s8, s9
	s_ashr_i32 s1, s0, 31
	s_lshl_b64 s[0:1], s[0:1], 11
	s_or_b64 s[0:1], s[0:1], s[22:23]
	s_add_u32 s64, s18, s0
	v_lshlrev_b32_e32 v142, 14, v134
	s_addc_u32 s65, s19, s1
	v_and_b32_e32 v142, 0xffff8000, v142
	s_add_u32 s0, s18, s62
	v_lshl_add_u32 v135, v135, 11, v142
	v_and_b32_e32 v134, 1, v134
	s_addc_u32 s8, s19, s63
	v_lshl_or_b32 v134, v134, 6, v135
	s_add_u32 s1, s0, 0x4e00100
	v_lshl_add_u32 v134, v141, 1, v134
	v_mov_b32_e32 v135, 0
	s_addc_u32 s8, s8, 0
	v_lshl_add_u64 v[134:135], s[64:65], 0, v[134:135]
	s_mov_b64 s[62:63], 0
	s_mov_b64 s[66:67], 0x8e40080
	s_mov_b64 s[68:69], 0x8e60080
	s_barrier

.LBB0_1043:
	s_add_u32 s27, s10, 0x2e00000
	s_addc_u32 s28, s11, 0
	s_add_u32 s29, s10, 0x4e00000
	s_addc_u32 s33, s11, 0
	s_add_u32 s35, s10, 0x2101000
	s_addc_u32 s39, s11, 0
	s_and_b32 s10, s12, 0xff
	s_cmp_lt_u32 s10, 4
	s_sext_i32_i8 s11, s12
	s_cselect_b32 s10, s28, s33
	s_cselect_b32 s30, s27, s29
	s_lshl_b32 s12, s12, 9
	s_and_b32 s12, s12, 0x600
	s_add_u32 s30, s30, s42
	s_addc_u32 s10, s10, s43
	s_add_u32 s62, s30, s12
	s_addc_u32 s63, s10, 0
	s_lshl_b32 s10, s11, 8
	s_ashr_i32 s11, s10, 31
	s_lshl_b64 s[10:11], s[10:11], 2
	s_add_u32 s60, s35, s10
	s_mov_b64 s[42:43], 0x80
	s_addc_u32 s61, s39, s11
	v_lshl_add_u64 v[10:11], v[2:3], 0, s[42:43]
	s_add_i32 m0, s9, 0x18000
	s_mov_b64 s[44:45], 0x20080
	global_load_lds_dwordx4 v[10:11], off
	v_lshl_add_u64 v[10:11], v[2:3], 0, s[44:45]
	s_add_i32 m0, s9, 0x1a000
	s_add_i32 s72, s9, 0x8000
	global_load_lds_dwordx4 v[10:11], off
	v_lshl_add_u64 v[10:11], v[4:5], 0, s[42:43]
	s_mov_b32 m0, s72
	s_add_i32 s73, s9, 0xa000
	global_load_lds_dwordx4 v[10:11], off
	v_lshl_add_u64 v[4:5], v[4:5], 0, s[44:45]
	s_mov_b32 m0, s73
	s_mov_b64 s[46:47], 0x40080
	global_load_lds_dwordx4 v[4:5], off
	v_lshl_add_u64 v[4:5], v[2:3], 0, s[46:47]
	s_add_i32 m0, s9, 0x1c000
	s_mov_b64 s[48:49], 0x60080
	global_load_lds_dwordx4 v[4:5], off
	v_lshl_add_u64 v[2:3], v[2:3], 0, s[48:49]
	s_add_i32 m0, s9, 0x1e000
	v_bfe_u32 v153, v6, 4, 2
	global_load_lds_dwordx4 v[2:3], off
	s_waitcnt vmcnt(10)
	s_barrier
	s_lshl_b32 s1, s1, 5
	v_and_b32_e32 v152, 15, v6
	v_lshlrev_b32_e32 v2, 4, v153
	v_lshlrev_b32_e32 v3, 2, v6
	s_and_b32 s75, s1, 0x60
	v_lshl_or_b32 v2, v152, 6, v2
	s_lshl_b32 s10, s13, 13
	v_and_b32_e32 v3, 32, v3
	s_lshl_b32 s1, s75, 7
	v_bitop3_b32 v4, v2, s10, v3 bitop3:0xde
	v_bitop3_b32 v154, v2, s1, v3 bitop3:0xde
	v_lshlrev_b32_e32 v2, 14, v8
	s_lshl_b32 s74, s13, 6
	v_and_b32_e32 v2, 0xffff8000, v2
	s_waitcnt vmcnt(6)
	s_cmpk_lt_u32 s0, 0x100
	v_lshl_add_u32 v2, v7, 11, v2
	v_and_b32_e32 v3, 1, v8
	s_cselect_b64 s[50:51], -1, 0
	v_lshl_or_b32 v2, v3, 6, v2
	s_add_i32 s78, 0, 0x10000
	s_add_i32 s79, 0, 0x14000
	s_ashr_i32 s76, s90, 31
	s_mov_b32 s77, s90
	v_lshl_add_u32 v142, v9, 1, v2
	v_mov_b32_e32 v143, v139
	v_mov_b64_e32 v[144:145], 0x200
	v_mov_b64_e32 v[146:147], 0x1ff
	v_add_u32_e32 v155, s78, v154
	v_add_u32_e32 v156, 0, v4
	v_add_u32_e32 v157, s79, v154
	s_lshl_b32 s40, s75, 1
	s_mov_b32 s80, 0x48000
	s_mov_b32 s81, 0x50000
	s_mov_b32 s82, s41
	s_barrier
	s_branch .LBB0_1046

.LBB0_1128:
	s_add_i32 s4, 0, 0x18000
	s_mov_b64 s[8:9], 0x80
	s_add_i32 s15, s4, s25
	v_lshl_add_u64 v[6:7], v[26:27], 0, s[8:9]
	s_mov_b32 m0, s15
	s_mov_b64 s[26:27], 0x20080
	s_add_i32 s22, s15, 0x2000
	global_load_lds_dwordx4 v[6:7], off
	v_lshl_add_u64 v[16:17], v[26:27], 0, s[26:27]
	s_mov_b32 m0, s22
	s_add_i32 s10, s23, 0x8000
	global_load_lds_dwordx4 v[16:17], off
	v_lshl_add_u64 v[2:3], v[22:23], 0, s[8:9]
	s_mov_b32 m0, s10
	s_add_i32 s11, s23, 0xa000
	s_add_i32 s5, 0, 0x1c000
	global_load_lds_dwordx4 v[2:3], off
	v_lshl_add_u64 v[4:5], v[22:23], 0, s[26:27]
	s_mov_b32 m0, s11
	s_mov_b64 s[30:31], 0x40080
	s_add_i32 s1, s5, s25
	global_load_lds_dwordx4 v[4:5], off
	v_lshl_add_u64 v[10:11], v[26:27], 0, s[30:31]
	s_mov_b32 m0, s1
	s_mov_b64 s[36:37], 0x60080
	s_add_i32 s9, s1, 0x2000
	global_load_lds_dwordx4 v[10:11], off
	v_lshl_add_u64 v[12:13], v[26:27], 0, s[36:37]
	s_mov_b32 m0, s9
	v_bfe_u32 v131, v30, 4, 2
	global_load_lds_dwordx4 v[12:13], off
	s_waitcnt vmcnt(10)
	s_barrier
	v_and_b32_e32 v130, 15, v30
	v_lshlrev_b32_e32 v31, 4, v131
	v_lshlrev_b32_e32 v30, 2, v30
	s_and_b32 s8, s6, 3
	v_lshl_or_b32 v31, v130, 6, v31
	s_lshl_b32 s6, s3, 13
	v_and_b32_e32 v30, 32, v30
	v_bitop3_b32 v32, v31, s6, v30 bitop3:0xde
	s_lshl_b32 s6, s8, 12
	v_bitop3_b32 v31, v31, s6, v30 bitop3:0xde
	s_add_i32 s6, 0, 0x10000
	v_add_u32_e32 v228, s6, v31
	s_waitcnt vmcnt(6)
	s_barrier
	v_add_u32_e32 v30, 0, v32
	ds_read_b128 v[32:35], v228
	ds_read_b128 v[36:39], v228 offset:1024
	ds_read_b128 v[40:43], v228 offset:2048
	ds_read_b128 v[44:47], v228 offset:3072
	s_add_i32 s7, 0, 0x14000
	s_add_i32 s27, s6, s25
	s_add_i32 s26, s7, s25
	v_add_u32_e32 v229, s7, v31
	v_add_u32_e32 v232, s4, v31
	v_add_u32_e32 v31, s5, v31
	s_add_i32 s33, s23, 0xc000
	s_add_i32 s29, s23, 0xe000
	s_add_i32 s28, s27, 0x2000
	s_add_i32 s25, s26, 0x2000
	s_cmpk_gt_u32 s0, 0xff
	s_mov_b32 m0, s33
	v_lshl_add_u64 v[80:81], v[22:23], 0, s[30:31]
	ds_read_b128 v[48:51], v30
	ds_read_b128 v[52:55], v30 offset:1024
	ds_read_b128 v[56:59], v30 offset:2048
	ds_read_b128 v[60:63], v30 offset:3072
	ds_read_b128 v[64:67], v30 offset:4096
	ds_read_b128 v[68:71], v30 offset:5120
	ds_read_b128 v[72:75], v30 offset:6144
	ds_read_b128 v[76:79], v30 offset:7168
	global_load_lds_dwordx4 v[80:81], off
	v_lshl_add_u64 v[80:81], v[22:23], 0, s[36:37]
	s_mov_b32 m0, s29
	s_nop 0
	global_load_lds_dwordx4 v[80:81], off
	s_waitcnt lgkmcnt(8)
	s_barrier
	s_waitcnt lgkmcnt(0)
	s_setprio 1
	s_waitcnt lgkmcnt(0)
	v_mfma_f32_16x16x32_bf16 v[80:83], v[32:35], v[48:51], 0
	v_mfma_f32_16x16x32_bf16 v[84:87], v[40:43], v[48:51], 0
	v_mfma_f32_16x16x32_bf16 v[88:91], v[32:35], v[56:59], 0
	v_mfma_f32_16x16x32_bf16 v[92:95], v[40:43], v[56:59], 0
	v_mfma_f32_16x16x32_bf16 v[96:99], v[32:35], v[64:67], 0
	v_mfma_f32_16x16x32_bf16 v[100:103], v[40:43], v[64:67], 0
	v_mfma_f32_16x16x32_bf16 v[104:107], v[32:35], v[72:75], 0
	v_mfma_f32_16x16x32_bf16 v[108:111], v[40:43], v[72:75], 0
	v_mfma_f32_16x16x32_bf16 v[80:83], v[36:39], v[52:55], v[80:83]
	v_mfma_f32_16x16x32_bf16 v[84:87], v[44:47], v[52:55], v[84:87]
	v_mfma_f32_16x16x32_bf16 v[88:91], v[36:39], v[60:63], v[88:91]
	v_mfma_f32_16x16x32_bf16 v[92:95], v[44:47], v[60:63], v[92:95]
	v_mfma_f32_16x16x32_bf16 v[96:99], v[36:39], v[68:71], v[96:99]
	v_mfma_f32_16x16x32_bf16 v[100:103], v[44:47], v[68:71], v[100:103]
	v_mfma_f32_16x16x32_bf16 v[104:107], v[36:39], v[76:79], v[104:107]
	v_mfma_f32_16x16x32_bf16 v[108:111], v[44:47], v[76:79], v[108:111]
	s_setprio 0
	s_barrier
	s_mov_b64 s[30:31], 0x100
	s_mov_b32 m0, s27
	v_lshl_add_u64 v[128:129], v[26:27], 0, s[30:31]
	s_mov_b64 s[36:37], 0x20100
	ds_read_b128 v[112:115], v229
	ds_read_b128 v[116:119], v229 offset:1024
	ds_read_b128 v[120:123], v229 offset:2048
	ds_read_b128 v[124:127], v229 offset:3072
	global_load_lds_dwordx4 v[128:129], off
	v_lshl_add_u64 v[128:129], v[26:27], 0, s[36:37]
	s_mov_b32 m0, s28
	s_nop 0
	global_load_lds_dwordx4 v[128:129], off
	s_barrier
	s_waitcnt lgkmcnt(0)
	s_setprio 1
	s_waitcnt lgkmcnt(0)
	v_mfma_f32_16x16x32_bf16 v[132:135], v[112:115], v[48:51], 0
	v_mfma_f32_16x16x32_bf16 v[48:51], v[120:123], v[48:51], 0
	v_mfma_f32_16x16x32_bf16 v[132:135], v[116:119], v[52:55], v[132:135]
	v_mfma_f32_16x16x32_bf16 v[48:51], v[124:127], v[52:55], v[48:51]
	v_mfma_f32_16x16x32_bf16 v[52:55], v[112:115], v[56:59], 0
	v_mfma_f32_16x16x32_bf16 v[56:59], v[120:123], v[56:59], 0
	v_mfma_f32_16x16x32_bf16 v[52:55], v[116:119], v[60:63], v[52:55]
	v_mfma_f32_16x16x32_bf16 v[56:59], v[124:127], v[60:63], v[56:59]
	v_mfma_f32_16x16x32_bf16 v[60:63], v[112:115], v[64:67], 0
	v_mfma_f32_16x16x32_bf16 v[64:67], v[120:123], v[64:67], 0
	v_mfma_f32_16x16x32_bf16 v[60:63], v[116:119], v[68:71], v[60:63]
	v_mfma_f32_16x16x32_bf16 v[64:67], v[124:127], v[68:71], v[64:67]
	v_mfma_f32_16x16x32_bf16 v[68:71], v[112:115], v[72:75], 0
	v_mfma_f32_16x16x32_bf16 v[72:75], v[120:123], v[72:75], 0
	v_mfma_f32_16x16x32_bf16 v[68:71], v[116:119], v[76:79], v[68:71]
	v_mfma_f32_16x16x32_bf16 v[72:75], v[124:127], v[76:79], v[72:75]
	s_setprio 0
	s_mov_b32 m0, s23
	v_lshl_add_u64 v[128:129], v[22:23], 0, s[30:31]
	s_barrier
	ds_read_b128 v[76:79], v30 offset:16384
	ds_read_b128 v[136:139], v30 offset:17408
	ds_read_b128 v[140:143], v30 offset:18432
	ds_read_b128 v[144:147], v30 offset:19456
	ds_read_b128 v[148:151], v30 offset:20480
	ds_read_b128 v[152:155], v30 offset:21504
	ds_read_b128 v[156:159], v30 offset:22528
	ds_read_b128 v[160:163], v30 offset:23552
	global_load_lds_dwordx4 v[128:129], off
	v_lshl_add_u64 v[128:129], v[22:23], 0, s[36:37]
	s_mov_b32 m0, s24
	s_nop 0
	global_load_lds_dwordx4 v[128:129], off
	s_barrier
	s_waitcnt lgkmcnt(0)
	s_setprio 1
	s_waitcnt lgkmcnt(0)
	v_mfma_f32_16x16x32_bf16 v[164:167], v[32:35], v[76:79], 0
	v_mfma_f32_16x16x32_bf16 v[172:175], v[32:35], v[140:143], 0
	v_mfma_f32_16x16x32_bf16 v[180:183], v[32:35], v[148:151], 0
	v_mfma_f32_16x16x32_bf16 v[32:35], v[32:35], v[156:159], 0
	v_mfma_f32_16x16x32_bf16 v[164:167], v[36:39], v[136:139], v[164:167]
	v_mfma_f32_16x16x32_bf16 v[172:175], v[36:39], v[144:147], v[172:175]
	v_mfma_f32_16x16x32_bf16 v[180:183], v[36:39], v[152:155], v[180:183]
	v_mfma_f32_16x16x32_bf16 v[32:35], v[36:39], v[160:163], v[32:35]
	v_mfma_f32_16x16x32_bf16 v[36:39], v[40:43], v[156:159], 0
	v_mfma_f32_16x16x32_bf16 v[168:171], v[40:43], v[76:79], 0
	v_mfma_f32_16x16x32_bf16 v[176:179], v[40:43], v[140:143], 0
	v_mfma_f32_16x16x32_bf16 v[184:187], v[40:43], v[148:151], 0
	v_mfma_f32_16x16x32_bf16 v[36:39], v[44:47], v[160:163], v[36:39]
	v_mfma_f32_16x16x32_bf16 v[168:171], v[44:47], v[136:139], v[168:171]
	v_mfma_f32_16x16x32_bf16 v[176:179], v[44:47], v[144:147], v[176:179]
	v_mfma_f32_16x16x32_bf16 v[184:187], v[44:47], v[152:155], v[184:187]
	s_setprio 0
	s_barrier
	s_mov_b64 s[30:31], 0x40100
	s_mov_b32 m0, s26
	v_lshl_add_u64 v[40:41], v[26:27], 0, s[30:31]
	s_mov_b64 s[36:37], 0x60100
	global_load_lds_dwordx4 v[40:41], off
	v_lshl_add_u64 v[40:41], v[26:27], 0, s[36:37]
	s_mov_b32 m0, s25
	s_nop 0
	global_load_lds_dwordx4 v[40:41], off
	s_waitcnt vmcnt(6)
	s_barrier
	s_setprio 1
	v_mfma_f32_16x16x32_bf16 v[40:43], v[112:115], v[76:79], 0
	v_mfma_f32_16x16x32_bf16 v[44:47], v[120:123], v[76:79], 0
	v_mfma_f32_16x16x32_bf16 v[40:43], v[116:119], v[136:139], v[40:43]
	v_mfma_f32_16x16x32_bf16 v[44:47], v[124:127], v[136:139], v[44:47]
	v_mfma_f32_16x16x32_bf16 v[76:79], v[112:115], v[140:143], 0
	v_mfma_f32_16x16x32_bf16 v[136:139], v[120:123], v[140:143], 0
	v_mfma_f32_16x16x32_bf16 v[140:143], v[112:115], v[148:151], 0
	v_mfma_f32_16x16x32_bf16 v[112:115], v[112:115], v[156:159], 0
	v_mfma_f32_16x16x32_bf16 v[76:79], v[116:119], v[144:147], v[76:79]
	v_mfma_f32_16x16x32_bf16 v[140:143], v[116:119], v[152:155], v[140:143]
	v_mfma_f32_16x16x32_bf16 v[112:115], v[116:119], v[160:163], v[112:115]
	v_mfma_f32_16x16x32_bf16 v[116:119], v[120:123], v[156:159], 0
	v_mfma_f32_16x16x32_bf16 v[136:139], v[124:127], v[144:147], v[136:139]
	v_mfma_f32_16x16x32_bf16 v[144:147], v[120:123], v[148:151], 0
	v_mfma_f32_16x16x32_bf16 v[116:119], v[124:127], v[160:163], v[116:119]
	v_mfma_f32_16x16x32_bf16 v[144:147], v[124:127], v[152:155], v[144:147]
	s_setprio 0
	s_barrier
	ds_read_b128 v[120:123], v232
	ds_read_b128 v[124:127], v232 offset:1024
	ds_read_b128 v[148:151], v232 offset:2048
	ds_read_b128 v[152:155], v232 offset:3072
	s_mov_b32 m0, s14
	v_lshl_add_u64 v[128:129], v[22:23], 0, s[30:31]
	ds_read_b128 v[156:159], v30 offset:32768
	ds_read_b128 v[160:163], v30 offset:33792
	ds_read_b128 v[188:191], v30 offset:34816
	ds_read_b128 v[192:195], v30 offset:35840
	ds_read_b128 v[196:199], v30 offset:36864
	ds_read_b128 v[200:203], v30 offset:37888
	ds_read_b128 v[204:207], v30 offset:38912
	ds_read_b128 v[208:211], v30 offset:39936
	global_load_lds_dwordx4 v[128:129], off
	v_lshl_add_u64 v[128:129], v[22:23], 0, s[36:37]
	s_mov_b32 m0, s21
	s_nop 0
	global_load_lds_dwordx4 v[128:129], off
	s_waitcnt lgkmcnt(8)
	s_barrier
	s_waitcnt lgkmcnt(0)
	s_setprio 1
	s_waitcnt lgkmcnt(0)
	v_mfma_f32_16x16x32_bf16 v[80:83], v[120:123], v[156:159], v[80:83]
	v_mfma_f32_16x16x32_bf16 v[84:87], v[148:151], v[156:159], v[84:87]
	v_mfma_f32_16x16x32_bf16 v[88:91], v[120:123], v[188:191], v[88:91]
	v_mfma_f32_16x16x32_bf16 v[92:95], v[148:151], v[188:191], v[92:95]
	v_mfma_f32_16x16x32_bf16 v[96:99], v[120:123], v[196:199], v[96:99]
	v_mfma_f32_16x16x32_bf16 v[100:103], v[148:151], v[196:199], v[100:103]
	v_mfma_f32_16x16x32_bf16 v[104:107], v[120:123], v[204:207], v[104:107]
	v_mfma_f32_16x16x32_bf16 v[108:111], v[148:151], v[204:207], v[108:111]
	v_mfma_f32_16x16x32_bf16 v[80:83], v[124:127], v[160:163], v[80:83]
	v_mfma_f32_16x16x32_bf16 v[84:87], v[152:155], v[160:163], v[84:87]
	v_mfma_f32_16x16x32_bf16 v[88:91], v[124:127], v[192:195], v[88:91]
	v_mfma_f32_16x16x32_bf16 v[92:95], v[152:155], v[192:195], v[92:95]
	v_mfma_f32_16x16x32_bf16 v[96:99], v[124:127], v[200:203], v[96:99]
	v_mfma_f32_16x16x32_bf16 v[100:103], v[152:155], v[200:203], v[100:103]
	v_mfma_f32_16x16x32_bf16 v[104:107], v[124:127], v[208:211], v[104:107]
	v_mfma_f32_16x16x32_bf16 v[108:111], v[152:155], v[208:211], v[108:111]
	s_setprio 0
	s_barrier
	s_mov_b64 s[30:31], 0x180
	s_mov_b32 m0, s15
	v_lshl_add_u64 v[128:129], v[26:27], 0, s[30:31]
	s_mov_b64 s[36:37], 0x20180
	ds_read_b128 v[212:215], v31
	ds_read_b128 v[216:219], v31 offset:1024
	ds_read_b128 v[220:223], v31 offset:2048
	ds_read_b128 v[224:227], v31 offset:3072
	global_load_lds_dwordx4 v[128:129], off
	v_lshl_add_u64 v[128:129], v[26:27], 0, s[36:37]
	s_mov_b32 m0, s22
	s_nop 0
	global_load_lds_dwordx4 v[128:129], off
	s_barrier
	s_waitcnt lgkmcnt(0)
	s_setprio 1
	s_waitcnt lgkmcnt(0)
	v_mfma_f32_16x16x32_bf16 v[48:51], v[220:223], v[156:159], v[48:51]
	v_mfma_f32_16x16x32_bf16 v[52:55], v[212:215], v[188:191], v[52:55]
	v_mfma_f32_16x16x32_bf16 v[56:59], v[220:223], v[188:191], v[56:59]
	v_mfma_f32_16x16x32_bf16 v[60:63], v[212:215], v[196:199], v[60:63]
	v_mfma_f32_16x16x32_bf16 v[64:67], v[220:223], v[196:199], v[64:67]
	v_mfma_f32_16x16x32_bf16 v[68:71], v[212:215], v[204:207], v[68:71]
	v_mfma_f32_16x16x32_bf16 v[72:75], v[220:223], v[204:207], v[72:75]
	v_mfma_f32_16x16x32_bf16 v[132:135], v[212:215], v[156:159], v[132:135]
	v_mfma_f32_16x16x32_bf16 v[48:51], v[224:227], v[160:163], v[48:51]
	v_mfma_f32_16x16x32_bf16 v[52:55], v[216:219], v[192:195], v[52:55]
	v_mfma_f32_16x16x32_bf16 v[56:59], v[224:227], v[192:195], v[56:59]
	v_mfma_f32_16x16x32_bf16 v[60:63], v[216:219], v[200:203], v[60:63]
	v_mfma_f32_16x16x32_bf16 v[64:67], v[224:227], v[200:203], v[64:67]
	v_mfma_f32_16x16x32_bf16 v[68:71], v[216:219], v[208:211], v[68:71]
	v_mfma_f32_16x16x32_bf16 v[72:75], v[224:227], v[208:211], v[72:75]
	v_mfma_f32_16x16x32_bf16 v[132:135], v[216:219], v[160:163], v[132:135]
	s_setprio 0
	s_mov_b32 m0, s10
	v_lshl_add_u64 v[128:129], v[22:23], 0, s[30:31]
	s_barrier
	ds_read_b128 v[156:159], v30 offset:49152
	ds_read_b128 v[160:163], v30 offset:50176
	ds_read_b128 v[188:191], v30 offset:51200
	ds_read_b128 v[192:195], v30 offset:52224
	ds_read_b128 v[196:199], v30 offset:53248
	ds_read_b128 v[200:203], v30 offset:54272
	ds_read_b128 v[204:207], v30 offset:55296
	ds_read_b128 v[208:211], v30 offset:56320
	global_load_lds_dwordx4 v[128:129], off
	v_lshl_add_u64 v[128:129], v[22:23], 0, s[36:37]
	s_mov_b32 m0, s11
	s_nop 0
	global_load_lds_dwordx4 v[128:129], off
	s_barrier
	s_waitcnt lgkmcnt(0)
	s_setprio 1
	s_waitcnt lgkmcnt(0)
	v_mfma_f32_16x16x32_bf16 v[32:35], v[120:123], v[204:207], v[32:35]
	v_mfma_f32_16x16x32_bf16 v[36:39], v[148:151], v[204:207], v[36:39]
	v_mfma_f32_16x16x32_bf16 v[164:167], v[120:123], v[156:159], v[164:167]
	v_mfma_f32_16x16x32_bf16 v[168:171], v[148:151], v[156:159], v[168:171]
	v_mfma_f32_16x16x32_bf16 v[172:175], v[120:123], v[188:191], v[172:175]
	v_mfma_f32_16x16x32_bf16 v[176:179], v[148:151], v[188:191], v[176:179]
	v_mfma_f32_16x16x32_bf16 v[180:183], v[120:123], v[196:199], v[180:183]
	v_mfma_f32_16x16x32_bf16 v[184:187], v[148:151], v[196:199], v[184:187]
	v_mfma_f32_16x16x32_bf16 v[32:35], v[124:127], v[208:211], v[32:35]
	v_mfma_f32_16x16x32_bf16 v[36:39], v[152:155], v[208:211], v[36:39]
	v_mfma_f32_16x16x32_bf16 v[164:167], v[124:127], v[160:163], v[164:167]
	v_mfma_f32_16x16x32_bf16 v[168:171], v[152:155], v[160:163], v[168:171]
	v_mfma_f32_16x16x32_bf16 v[172:175], v[124:127], v[192:195], v[172:175]
	v_mfma_f32_16x16x32_bf16 v[176:179], v[152:155], v[192:195], v[176:179]
	v_mfma_f32_16x16x32_bf16 v[180:183], v[124:127], v[200:203], v[180:183]
	v_mfma_f32_16x16x32_bf16 v[184:187], v[152:155], v[200:203], v[184:187]
	s_setprio 0
	s_barrier
	s_mov_b64 s[30:31], 0x40180
	s_mov_b32 m0, s1
	v_lshl_add_u64 v[120:121], v[26:27], 0, s[30:31]
	s_mov_b64 s[36:37], 0x60180
	global_load_lds_dwordx4 v[120:121], off
	v_lshl_add_u64 v[120:121], v[26:27], 0, s[36:37]
	s_mov_b32 m0, s9
	s_nop 0
	global_load_lds_dwordx4 v[120:121], off
	s_waitcnt vmcnt(6)
	s_barrier
	s_setprio 1
	v_mfma_f32_16x16x32_bf16 v[40:43], v[212:215], v[156:159], v[40:43]
	v_mfma_f32_16x16x32_bf16 v[44:47], v[220:223], v[156:159], v[44:47]
	v_mfma_f32_16x16x32_bf16 v[76:79], v[212:215], v[188:191], v[76:79]
	v_mfma_f32_16x16x32_bf16 v[120:123], v[220:223], v[188:191], v[136:139]
	v_mfma_f32_16x16x32_bf16 v[124:127], v[212:215], v[196:199], v[140:143]
	v_mfma_f32_16x16x32_bf16 v[112:115], v[212:215], v[204:207], v[112:115]
	v_mfma_f32_16x16x32_bf16 v[116:119], v[220:223], v[204:207], v[116:119]
	v_mfma_f32_16x16x32_bf16 v[40:43], v[216:219], v[160:163], v[40:43]
	v_mfma_f32_16x16x32_bf16 v[44:47], v[224:227], v[160:163], v[44:47]
	v_mfma_f32_16x16x32_bf16 v[76:79], v[216:219], v[192:195], v[76:79]
	v_mfma_f32_16x16x32_bf16 v[120:123], v[224:227], v[192:195], v[120:123]
	v_mfma_f32_16x16x32_bf16 v[124:127], v[216:219], v[200:203], v[124:127]
	v_mfma_f32_16x16x32_bf16 v[136:139], v[220:223], v[196:199], v[144:147]
	v_mfma_f32_16x16x32_bf16 v[112:115], v[216:219], v[208:211], v[112:115]
	v_mfma_f32_16x16x32_bf16 v[116:119], v[224:227], v[208:211], v[116:119]
	v_mfma_f32_16x16x32_bf16 v[136:139], v[224:227], v[200:203], v[136:139]
	s_setprio 0
	s_barrier
	ds_read_b128 v[140:143], v228
	ds_read_b128 v[144:147], v228 offset:1024
	ds_read_b128 v[148:151], v228 offset:2048
	ds_read_b128 v[152:155], v228 offset:3072
	s_mov_b32 m0, s33
	v_lshl_add_u64 v[128:129], v[22:23], 0, s[30:31]
	ds_read_b128 v[156:159], v30
	ds_read_b128 v[160:163], v30 offset:1024
	ds_read_b128 v[188:191], v30 offset:2048
	ds_read_b128 v[192:195], v30 offset:3072
	ds_read_b128 v[196:199], v30 offset:4096
	ds_read_b128 v[200:203], v30 offset:5120
	ds_read_b128 v[204:207], v30 offset:6144
	ds_read_b128 v[208:211], v30 offset:7168
	global_load_lds_dwordx4 v[128:129], off
	v_lshl_add_u64 v[128:129], v[22:23], 0, s[36:37]
	s_mov_b32 m0, s29
	s_nop 0
	global_load_lds_dwordx4 v[128:129], off
	s_waitcnt lgkmcnt(8)
	s_barrier
	s_waitcnt lgkmcnt(0)
	s_setprio 1
	s_waitcnt lgkmcnt(0)
	v_mfma_f32_16x16x32_bf16 v[96:99], v[140:143], v[196:199], v[96:99]
	v_mfma_f32_16x16x32_bf16 v[212:215], v[144:147], v[200:203], v[96:99]
	v_mfma_f32_16x16x32_bf16 v[96:99], v[148:151], v[196:199], v[100:103]
	v_mfma_f32_16x16x32_bf16 v[216:219], v[152:155], v[200:203], v[96:99]
	v_mfma_f32_16x16x32_bf16 v[96:99], v[140:143], v[204:207], v[104:107]
	v_mfma_f32_16x16x32_bf16 v[80:83], v[140:143], v[156:159], v[80:83]
	v_mfma_f32_16x16x32_bf16 v[84:87], v[148:151], v[156:159], v[84:87]
	v_mfma_f32_16x16x32_bf16 v[88:91], v[140:143], v[188:191], v[88:91]
	v_mfma_f32_16x16x32_bf16 v[92:95], v[148:151], v[188:191], v[92:95]
	v_mfma_f32_16x16x32_bf16 v[220:223], v[144:147], v[208:211], v[96:99]
	v_mfma_f32_16x16x32_bf16 v[96:99], v[148:151], v[204:207], v[108:111]
	v_mfma_f32_16x16x32_bf16 v[80:83], v[144:147], v[160:163], v[80:83]
	v_mfma_f32_16x16x32_bf16 v[84:87], v[152:155], v[160:163], v[84:87]
	v_mfma_f32_16x16x32_bf16 v[88:91], v[144:147], v[192:195], v[88:91]
	v_mfma_f32_16x16x32_bf16 v[92:95], v[152:155], v[192:195], v[92:95]
	v_mfma_f32_16x16x32_bf16 v[106:109], v[152:155], v[208:211], v[96:99]
	s_setprio 0
	s_barrier
	s_mov_b32 m0, s27
	ds_read_b128 v[96:99], v229
	ds_read_b128 v[100:103], v229 offset:1024
	ds_read_b128 v[224:227], v229 offset:2048
	ds_read_b128 v[228:231], v229 offset:3072
	global_load_lds_dwordx4 v[26:27], off
	s_mov_b32 m0, s28
	s_nop 0
	global_load_lds_dwordx4 v[28:29], off
	s_barrier
	s_waitcnt lgkmcnt(0)
	s_setprio 1
	s_waitcnt lgkmcnt(0)
	v_mfma_f32_16x16x32_bf16 v[48:51], v[224:227], v[156:159], v[48:51]
	v_mfma_f32_16x16x32_bf16 v[26:29], v[96:99], v[156:159], v[132:135]
	v_mfma_f32_16x16x32_bf16 v[132:135], v[228:231], v[160:163], v[48:51]
	v_mfma_f32_16x16x32_bf16 v[48:51], v[96:99], v[188:191], v[52:55]
	v_mfma_f32_16x16x32_bf16 v[156:159], v[100:103], v[192:195], v[48:51]
	v_mfma_f32_16x16x32_bf16 v[48:51], v[224:227], v[188:191], v[56:59]
	v_mfma_f32_16x16x32_bf16 v[26:29], v[100:103], v[160:163], v[26:29]
	v_mfma_f32_16x16x32_bf16 v[160:163], v[228:231], v[192:195], v[48:51]
	v_mfma_f32_16x16x32_bf16 v[48:51], v[96:99], v[196:199], v[60:63]
	v_mfma_f32_16x16x32_bf16 v[58:61], v[100:103], v[200:203], v[48:51]
	v_mfma_f32_16x16x32_bf16 v[48:51], v[224:227], v[196:199], v[64:67]
	v_mfma_f32_16x16x32_bf16 v[62:65], v[228:231], v[200:203], v[48:51]
	v_mfma_f32_16x16x32_bf16 v[48:51], v[96:99], v[204:207], v[68:71]
	v_mfma_f32_16x16x32_bf16 v[66:69], v[100:103], v[208:211], v[48:51]
	v_mfma_f32_16x16x32_bf16 v[48:51], v[224:227], v[204:207], v[72:75]
	v_mfma_f32_16x16x32_bf16 v[70:73], v[228:231], v[208:211], v[48:51]
	s_setprio 0
	s_mov_b32 m0, s23
	s_barrier
	s_nop 3
	ds_read_b128 v[48:51], v30 offset:16384
	ds_read_b128 v[52:55], v30 offset:17408
	ds_read_b128 v[188:191], v30 offset:18432
	ds_read_b128 v[192:195], v30 offset:19456
	ds_read_b128 v[196:199], v30 offset:20480
	ds_read_b128 v[200:203], v30 offset:21504
	ds_read_b128 v[204:207], v30 offset:22528
	ds_read_b128 v[208:211], v30 offset:23552
	global_load_lds_dwordx4 v[22:23], off
	s_mov_b32 m0, s24
	s_nop 0
	global_load_lds_dwordx4 v[24:25], off
	s_barrier
	s_waitcnt lgkmcnt(0)
	s_setprio 1
	s_waitcnt lgkmcnt(0)
	v_mfma_f32_16x16x32_bf16 v[22:25], v[140:143], v[48:51], v[164:167]
	v_mfma_f32_16x16x32_bf16 v[32:35], v[140:143], v[204:207], v[32:35]
	v_mfma_f32_16x16x32_bf16 v[22:25], v[144:147], v[52:55], v[22:25]
	v_mfma_f32_16x16x32_bf16 v[164:167], v[148:151], v[48:51], v[168:171]
	v_mfma_f32_16x16x32_bf16 v[168:171], v[140:143], v[188:191], v[172:175]
	v_mfma_f32_16x16x32_bf16 v[172:175], v[148:151], v[188:191], v[176:179]
	v_mfma_f32_16x16x32_bf16 v[176:179], v[140:143], v[196:199], v[180:183]
	v_mfma_f32_16x16x32_bf16 v[180:183], v[148:151], v[196:199], v[184:187]
	v_mfma_f32_16x16x32_bf16 v[140:143], v[144:147], v[208:211], v[32:35]
	v_mfma_f32_16x16x32_bf16 v[32:35], v[148:151], v[204:207], v[36:39]
	v_mfma_f32_16x16x32_bf16 v[164:167], v[152:155], v[52:55], v[164:167]
	v_mfma_f32_16x16x32_bf16 v[168:171], v[144:147], v[192:195], v[168:171]
	v_mfma_f32_16x16x32_bf16 v[172:175], v[152:155], v[192:195], v[172:175]
	v_mfma_f32_16x16x32_bf16 v[176:179], v[144:147], v[200:203], v[176:179]
	v_mfma_f32_16x16x32_bf16 v[180:183], v[152:155], v[200:203], v[180:183]
	v_mfma_f32_16x16x32_bf16 v[144:147], v[152:155], v[208:211], v[32:35]
	s_setprio 0
	s_barrier
	s_mov_b32 m0, s26
	s_nop 0
	global_load_lds_dwordx4 v[18:19], off
	s_mov_b32 m0, s25
	s_nop 0
	global_load_lds_dwordx4 v[20:21], off
	s_waitcnt vmcnt(6)
	s_barrier
	s_setprio 1
	v_mfma_f32_16x16x32_bf16 v[18:21], v[96:99], v[48:51], v[40:43]
	v_mfma_f32_16x16x32_bf16 v[148:151], v[100:103], v[52:55], v[18:21]
	v_mfma_f32_16x16x32_bf16 v[18:21], v[224:227], v[48:51], v[44:47]
	v_mfma_f32_16x16x32_bf16 v[42:45], v[228:231], v[52:55], v[18:21]
	v_mfma_f32_16x16x32_bf16 v[18:21], v[96:99], v[188:191], v[76:79]
	v_mfma_f32_16x16x32_bf16 v[46:49], v[100:103], v[192:195], v[18:21]
	v_mfma_f32_16x16x32_bf16 v[18:21], v[224:227], v[188:191], v[120:123]
	v_mfma_f32_16x16x32_bf16 v[152:155], v[228:231], v[192:195], v[18:21]
	v_mfma_f32_16x16x32_bf16 v[18:21], v[96:99], v[196:199], v[124:127]
	v_mfma_f32_16x16x32_bf16 v[184:187], v[100:103], v[200:203], v[18:21]
	v_mfma_f32_16x16x32_bf16 v[18:21], v[224:227], v[196:199], v[136:139]
	v_mfma_f32_16x16x32_bf16 v[136:139], v[228:231], v[200:203], v[18:21]
	v_mfma_f32_16x16x32_bf16 v[18:21], v[96:99], v[204:207], v[112:115]
	v_mfma_f32_16x16x32_bf16 v[188:191], v[100:103], v[208:211], v[18:21]
	v_mfma_f32_16x16x32_bf16 v[18:21], v[224:227], v[204:207], v[116:119]
	v_mfma_f32_16x16x32_bf16 v[192:195], v[228:231], v[208:211], v[18:21]
	s_setprio 0
	s_barrier
	ds_read_b128 v[196:199], v232
	ds_read_b128 v[200:203], v232 offset:1024
	ds_read_b128 v[204:207], v232 offset:2048
	ds_read_b128 v[208:211], v232 offset:3072
	s_mov_b32 m0, s14
	ds_read_b128 v[18:21], v30 offset:32768
	ds_read_b128 v[32:35], v30 offset:33792
	ds_read_b128 v[36:39], v30 offset:34816
	ds_read_b128 v[74:77], v30 offset:35840
	ds_read_b128 v[224:227], v30 offset:36864
	ds_read_b128 v[228:231], v30 offset:37888
	ds_read_b128 v[232:235], v30 offset:38912
	ds_read_b128 v[236:239], v30 offset:39936
	global_load_lds_dwordx4 v[8:9], off
	s_mov_b32 m0, s21
	s_nop 0
	global_load_lds_dwordx4 v[14:15], off
	s_waitcnt lgkmcnt(8)
	s_barrier
	s_waitcnt lgkmcnt(0)
	s_setprio 1
	s_waitcnt lgkmcnt(0)
	v_mfma_f32_16x16x32_bf16 v[50:53], v[196:199], v[18:21], v[80:83]
	v_mfma_f32_16x16x32_bf16 v[118:121], v[200:203], v[32:35], v[50:53]
	v_mfma_f32_16x16x32_bf16 v[50:53], v[204:207], v[18:21], v[84:87]
	v_mfma_f32_16x16x32_bf16 v[114:117], v[208:211], v[32:35], v[50:53]
	v_mfma_f32_16x16x32_bf16 v[50:53], v[196:199], v[36:39], v[88:91]
	v_mfma_f32_16x16x32_bf16 v[102:105], v[200:203], v[74:77], v[50:53]
	v_mfma_f32_16x16x32_bf16 v[50:53], v[204:207], v[36:39], v[92:95]
	v_mfma_f32_16x16x32_bf16 v[98:101], v[208:211], v[74:77], v[50:53]
	v_mfma_f32_16x16x32_bf16 v[50:53], v[196:199], v[224:227], v[212:215]
	v_mfma_f32_16x16x32_bf16 v[86:89], v[200:203], v[228:231], v[50:53]
	v_mfma_f32_16x16x32_bf16 v[50:53], v[204:207], v[224:227], v[216:219]
	v_mfma_f32_16x16x32_bf16 v[82:85], v[208:211], v[228:231], v[50:53]
	v_mfma_f32_16x16x32_bf16 v[50:53], v[196:199], v[232:235], v[220:223]
	v_mfma_f32_16x16x32_bf16 v[54:57], v[200:203], v[236:239], v[50:53]
	v_mfma_f32_16x16x32_bf16 v[50:53], v[204:207], v[232:235], v[106:109]
	v_mfma_f32_16x16x32_bf16 v[50:53], v[208:211], v[236:239], v[50:53]
	s_setprio 0
	s_barrier
	s_mov_b32 m0, s15
	ds_read_b128 v[212:215], v31
	ds_read_b128 v[216:219], v31 offset:1024
	ds_read_b128 v[220:223], v31 offset:2048
	ds_read_b128 v[240:243], v31 offset:3072
	global_load_lds_dwordx4 v[6:7], off
	s_mov_b32 m0, s22
	s_nop 0
	global_load_lds_dwordx4 v[16:17], off
	s_barrier
	s_waitcnt lgkmcnt(0)
	s_setprio 1
	s_waitcnt lgkmcnt(0)
	v_mfma_f32_16x16x32_bf16 v[6:9], v[212:215], v[18:21], v[26:29]
	v_mfma_f32_16x16x32_bf16 v[126:129], v[216:219], v[32:35], v[6:9]
	v_mfma_f32_16x16x32_bf16 v[6:9], v[220:223], v[18:21], v[132:135]
	v_mfma_f32_16x16x32_bf16 v[122:125], v[240:243], v[32:35], v[6:9]
	v_mfma_f32_16x16x32_bf16 v[6:9], v[212:215], v[36:39], v[156:159]
	v_mfma_f32_16x16x32_bf16 v[110:113], v[216:219], v[74:77], v[6:9]
	v_mfma_f32_16x16x32_bf16 v[6:9], v[220:223], v[36:39], v[160:163]
	v_mfma_f32_16x16x32_bf16 v[106:109], v[240:243], v[74:77], v[6:9]
	v_mfma_f32_16x16x32_bf16 v[6:9], v[212:215], v[224:227], v[58:61]
	v_mfma_f32_16x16x32_bf16 v[94:97], v[216:219], v[228:231], v[6:9]
	v_mfma_f32_16x16x32_bf16 v[6:9], v[220:223], v[224:227], v[62:65]
	v_mfma_f32_16x16x32_bf16 v[90:93], v[240:243], v[228:231], v[6:9]
	v_mfma_f32_16x16x32_bf16 v[6:9], v[212:215], v[232:235], v[66:69]
	v_mfma_f32_16x16x32_bf16 v[74:77], v[216:219], v[236:239], v[6:9]
	v_mfma_f32_16x16x32_bf16 v[6:9], v[220:223], v[232:235], v[70:73]
	v_mfma_f32_16x16x32_bf16 v[66:69], v[240:243], v[236:239], v[6:9]
	s_setprio 0
	s_mov_b32 m0, s10
	s_barrier
	ds_read_b128 v[14:17], v30 offset:49152
	ds_read_b128 v[26:29], v30 offset:50176
	ds_read_b128 v[132:135], v30 offset:51200
	ds_read_b128 v[156:159], v30 offset:52224
	ds_read_b128 v[160:163], v30 offset:53248
	ds_read_b128 v[224:227], v30 offset:54272
	ds_read_b128 v[228:231], v30 offset:55296
	ds_read_b128 v[232:235], v30 offset:56320
	global_load_lds_dwordx4 v[2:3], off
	s_mov_b32 m0, s11
	s_nop 0
	global_load_lds_dwordx4 v[4:5], off
	s_barrier
	s_waitcnt lgkmcnt(0)
	s_setprio 1
	s_waitcnt lgkmcnt(0)
	v_mfma_f32_16x16x32_bf16 v[2:5], v[196:199], v[14:17], v[22:25]
	v_mfma_f32_16x16x32_bf16 v[62:65], v[200:203], v[26:29], v[2:5]
	v_mfma_f32_16x16x32_bf16 v[2:5], v[204:207], v[14:17], v[164:167]
	v_mfma_f32_16x16x32_bf16 v[58:61], v[208:211], v[26:29], v[2:5]
	v_mfma_f32_16x16x32_bf16 v[2:5], v[196:199], v[132:135], v[168:171]
	v_mfma_f32_16x16x32_bf16 v[38:41], v[200:203], v[156:159], v[2:5]
	v_mfma_f32_16x16x32_bf16 v[2:5], v[204:207], v[132:135], v[172:175]
	v_mfma_f32_16x16x32_bf16 v[34:37], v[208:211], v[156:159], v[2:5]
	v_mfma_f32_16x16x32_bf16 v[2:5], v[196:199], v[160:163], v[176:179]
	v_mfma_f32_16x16x32_bf16 v[22:25], v[200:203], v[224:227], v[2:5]
	v_mfma_f32_16x16x32_bf16 v[2:5], v[204:207], v[160:163], v[180:183]
	v_mfma_f32_16x16x32_bf16 v[18:21], v[208:211], v[224:227], v[2:5]
	v_mfma_f32_16x16x32_bf16 v[2:5], v[196:199], v[228:231], v[140:143]
	v_mfma_f32_16x16x32_bf16 v[6:9], v[200:203], v[232:235], v[2:5]
	v_mfma_f32_16x16x32_bf16 v[2:5], v[204:207], v[228:231], v[144:147]
	v_mfma_f32_16x16x32_bf16 v[2:5], v[208:211], v[232:235], v[2:5]
	s_setprio 0
	s_barrier
	s_mov_b32 m0, s1
	s_nop 0
	global_load_lds_dwordx4 v[10:11], off
	s_mov_b32 m0, s9
	s_nop 0
	global_load_lds_dwordx4 v[12:13], off
	s_waitcnt vmcnt(6)
	s_barrier
	s_setprio 1
	v_mfma_f32_16x16x32_bf16 v[10:13], v[212:215], v[14:17], v[148:151]
	v_mfma_f32_16x16x32_bf16 v[78:81], v[216:219], v[26:29], v[10:13]
	v_mfma_f32_16x16x32_bf16 v[10:13], v[220:223], v[14:17], v[42:45]
	v_mfma_f32_16x16x32_bf16 v[70:73], v[240:243], v[26:29], v[10:13]
	v_mfma_f32_16x16x32_bf16 v[10:13], v[212:215], v[132:135], v[46:49]
	v_mfma_f32_16x16x32_bf16 v[46:49], v[216:219], v[156:159], v[10:13]
	v_mfma_f32_16x16x32_bf16 v[10:13], v[220:223], v[132:135], v[152:155]
	v_mfma_f32_16x16x32_bf16 v[42:45], v[240:243], v[156:159], v[10:13]
	v_mfma_f32_16x16x32_bf16 v[10:13], v[212:215], v[160:163], v[184:187]
	v_mfma_f32_16x16x32_bf16 v[30:33], v[216:219], v[224:227], v[10:13]
	v_mfma_f32_16x16x32_bf16 v[10:13], v[220:223], v[160:163], v[136:139]
	v_mfma_f32_16x16x32_bf16 v[26:29], v[240:243], v[224:227], v[10:13]
	v_mfma_f32_16x16x32_bf16 v[10:13], v[212:215], v[228:231], v[188:191]
	v_mfma_f32_16x16x32_bf16 v[14:17], v[216:219], v[232:235], v[10:13]
	v_mfma_f32_16x16x32_bf16 v[10:13], v[220:223], v[228:231], v[192:195]
	v_mfma_f32_16x16x32_bf16 v[10:13], v[240:243], v[232:235], v[10:13]
	s_setprio 0
	s_barrier
	s_cbranch_scc1 .LBB0_1130
	s_barrier

.LBB0_1168:
	v_bfe_u32 v134, v6, 4, 2
	v_and_b32_e32 v135, 15, v6
	v_lshlrev_b32_e32 v7, 4, v134
	v_lshlrev_b32_e32 v6, 2, v6
	s_lshl_b32 s24, s26, 6
	v_lshl_or_b32 v7, v135, 6, v7
	s_lshl_b32 s26, s26, 13
	v_and_b32_e32 v6, 32, v6
	s_lshl_b32 s1, s1, 5
	v_bitop3_b32 v8, v7, s26, v6 bitop3:0xde
	s_and_b32 s26, s1, 0x60
	s_lshl_b32 s1, s26, 7
	s_mov_b64 s[40:41], 0x80
	v_bitop3_b32 v9, v7, s1, v6 bitop3:0xde
	v_lshl_add_u64 v[6:7], v[2:3], 0, s[40:41]
	s_add_i32 m0, s8, 0x18000
	s_mov_b64 s[42:43], 0x8080
	global_load_lds_dwordx4 v[6:7], off
	v_lshl_add_u64 v[6:7], v[2:3], 0, s[42:43]
	s_add_i32 m0, s8, 0x1a000
	s_add_i32 s28, s8, 0x8000
	global_load_lds_dwordx4 v[6:7], off
	v_lshl_add_u64 v[6:7], v[4:5], 0, s[40:41]
	s_mov_b32 m0, s28
	s_add_i32 s29, s8, 0xa000
	global_load_lds_dwordx4 v[6:7], off
	v_lshl_add_u64 v[4:5], v[4:5], 0, s[42:43]
	s_mov_b32 m0, s29
	s_mov_b64 s[44:45], 0x10080
	global_load_lds_dwordx4 v[4:5], off
	v_lshl_add_u64 v[4:5], v[2:3], 0, s[44:45]
	s_add_i32 m0, s8, 0x1c000
	s_mov_b64 s[46:47], 0x18080
	global_load_lds_dwordx4 v[4:5], off
	v_lshl_add_u64 v[2:3], v[2:3], 0, s[46:47]
	s_add_i32 m0, s8, 0x1e000
	s_add_i32 s37, s6, s0
	global_load_lds_dwordx4 v[2:3], off
	s_waitcnt vmcnt(10)
	s_barrier
	s_waitcnt vmcnt(6)
	s_add_i32 s57, s7, s0
	s_add_i32 s59, s4, s0
	s_add_i32 s61, s5, s0
	s_mov_b64 s[52:53], 0
	s_mov_b64 s[48:49], -1
	s_mov_b64 s[50:51], 0x100
	s_add_i32 s33, s8, 0xc000
	s_add_i32 s35, s8, 0xe000
	s_add_i32 s56, s37, 0x2000
	s_add_i32 s58, s57, 0x2000
	s_add_i32 s60, s59, 0x2000
	s_add_i32 s62, s61, 0x2000
	v_add_u32_e32 v136, s6, v9
	v_add_u32_e32 v137, 0, v8
	v_add_u32_e32 v138, s7, v9
	v_add_u32_e32 v139, s4, v9
	v_add_u32_e32 v140, s5, v9
	v_mov_b32_e32 v2, v133
	v_mov_b32_e32 v3, v133
	v_mov_b32_e32 v4, v133
	v_mov_b32_e32 v5, v133
	v_mov_b32_e32 v6, v133
	v_mov_b32_e32 v7, v133
	v_mov_b32_e32 v8, v133
	v_mov_b32_e32 v9, v133
	v_mov_b32_e32 v10, v133
	v_mov_b32_e32 v11, v133
	v_mov_b32_e32 v12, v133
	v_mov_b32_e32 v13, v133
	v_mov_b32_e32 v14, v133
	v_mov_b32_e32 v15, v133
	v_mov_b32_e32 v16, v133
	v_mov_b32_e32 v17, v133
	v_mov_b32_e32 v18, v133
	v_mov_b32_e32 v19, v133
	v_mov_b32_e32 v20, v133
	v_mov_b32_e32 v21, v133
	v_mov_b32_e32 v22, v133
	v_mov_b32_e32 v23, v133
	v_mov_b32_e32 v24, v133
	v_mov_b32_e32 v25, v133
	v_mov_b32_e32 v26, v133
	v_mov_b32_e32 v27, v133
	v_mov_b32_e32 v28, v133
	v_mov_b32_e32 v29, v133
	v_mov_b32_e32 v30, v133
	v_mov_b32_e32 v31, v133
	v_mov_b32_e32 v32, v133
	v_mov_b32_e32 v33, v133
	v_mov_b32_e32 v54, v133
	v_mov_b32_e32 v55, v133
	v_mov_b32_e32 v56, v133
	v_mov_b32_e32 v57, v133
	v_mov_b32_e32 v62, v133
	v_mov_b32_e32 v63, v133
	v_mov_b32_e32 v64, v133
	v_mov_b32_e32 v65, v133
	v_mov_b32_e32 v74, v133
	v_mov_b32_e32 v75, v133
	v_mov_b32_e32 v76, v133
	v_mov_b32_e32 v77, v133
	v_mov_b32_e32 v78, v133
	v_mov_b32_e32 v79, v133
	v_mov_b32_e32 v80, v133
	v_mov_b32_e32 v81, v133
	v_mov_b32_e32 v82, v133
	v_mov_b32_e32 v83, v133
	v_mov_b32_e32 v84, v133
	v_mov_b32_e32 v85, v133
	v_mov_b32_e32 v86, v133
	v_mov_b32_e32 v87, v133
	v_mov_b32_e32 v88, v133
	v_mov_b32_e32 v89, v133
	v_mov_b32_e32 v90, v133
	v_mov_b32_e32 v91, v133
	v_mov_b32_e32 v92, v133
	v_mov_b32_e32 v93, v133
	v_mov_b32_e32 v94, v133
	v_mov_b32_e32 v95, v133
	v_mov_b32_e32 v96, v133
	v_mov_b32_e32 v97, v133
	v_mov_b32_e32 v34, v133
	v_mov_b32_e32 v35, v133
	v_mov_b32_e32 v36, v133
	v_mov_b32_e32 v37, v133
	v_mov_b32_e32 v38, v133
	v_mov_b32_e32 v39, v133
	v_mov_b32_e32 v40, v133
	v_mov_b32_e32 v41, v133
	v_mov_b32_e32 v42, v133
	v_mov_b32_e32 v43, v133
	v_mov_b32_e32 v44, v133
	v_mov_b32_e32 v45, v133
	v_mov_b32_e32 v46, v133
	v_mov_b32_e32 v47, v133
	v_mov_b32_e32 v48, v133
	v_mov_b32_e32 v49, v133
	v_mov_b32_e32 v50, v133
	v_mov_b32_e32 v51, v133
	v_mov_b32_e32 v52, v133
	v_mov_b32_e32 v53, v133
	v_mov_b32_e32 v58, v133
	v_mov_b32_e32 v59, v133
	v_mov_b32_e32 v60, v133
	v_mov_b32_e32 v61, v133
	v_mov_b32_e32 v66, v133
	v_mov_b32_e32 v67, v133
	v_mov_b32_e32 v68, v133
	v_mov_b32_e32 v69, v133
	v_mov_b32_e32 v70, v133
	v_mov_b32_e32 v71, v133
	v_mov_b32_e32 v72, v133
	v_mov_b32_e32 v73, v133
	v_mov_b32_e32 v98, v133
	v_mov_b32_e32 v99, v133
	v_mov_b32_e32 v100, v133
	v_mov_b32_e32 v101, v133
	v_mov_b32_e32 v102, v133
	v_mov_b32_e32 v103, v133
	v_mov_b32_e32 v104, v133
	v_mov_b32_e32 v105, v133
	v_mov_b32_e32 v106, v133
	v_mov_b32_e32 v107, v133
	v_mov_b32_e32 v108, v133
	v_mov_b32_e32 v109, v133
	v_mov_b32_e32 v110, v133
	v_mov_b32_e32 v111, v133
	v_mov_b32_e32 v112, v133
	v_mov_b32_e32 v113, v133
	v_mov_b32_e32 v114, v133
	v_mov_b32_e32 v115, v133
	v_mov_b32_e32 v116, v133
	v_mov_b32_e32 v117, v133
	v_mov_b32_e32 v118, v133
	v_mov_b32_e32 v119, v133
	v_mov_b32_e32 v120, v133
	v_mov_b32_e32 v121, v133
	v_mov_b32_e32 v122, v133
	v_mov_b32_e32 v123, v133
	v_mov_b32_e32 v124, v133
	v_mov_b32_e32 v125, v133
	v_mov_b32_e32 v126, v133
	v_mov_b32_e32 v127, v133
	v_mov_b32_e32 v128, v133
	v_mov_b32_e32 v129, v133
	s_barrier

.LBB0_1230:
	s_add_u32 s44, s46, 0x2e00000
	s_addc_u32 s45, s47, 0
	s_add_u32 s46, s46, 0x4e00000
	s_mov_b64 s[48:49], 0x80
	s_addc_u32 s47, s47, 0
	v_lshl_add_u64 v[8:9], v[2:3], 0, s[48:49]
	s_add_i32 m0, s78, 0x18000
	s_mov_b64 s[50:51], 0x8080
	global_load_lds_dwordx4 v[8:9], off
	v_lshl_add_u64 v[8:9], v[2:3], 0, s[50:51]
	s_add_i32 m0, s78, 0x1a000
	s_add_i32 s83, s78, 0x8000
	global_load_lds_dwordx4 v[8:9], off
	v_lshl_add_u64 v[8:9], v[4:5], 0, s[48:49]
	s_mov_b32 m0, s83
	s_mov_b64 s[52:53], 0x20080
	s_add_i32 s87, s78, 0xa000
	global_load_lds_dwordx4 v[8:9], off
	v_lshl_add_u64 v[4:5], v[4:5], 0, s[52:53]
	s_mov_b32 m0, s87
	s_mov_b64 s[54:55], 0x10080
	global_load_lds_dwordx4 v[4:5], off
	v_lshl_add_u64 v[4:5], v[2:3], 0, s[54:55]
	s_add_i32 m0, s78, 0x1c000
	s_mov_b64 s[56:57], 0x18080
	global_load_lds_dwordx4 v[4:5], off
	v_lshl_add_u64 v[2:3], v[2:3], 0, s[56:57]
	s_add_i32 m0, s78, 0x1e000
	v_bfe_u32 v172, v6, 4, 2
	global_load_lds_dwordx4 v[2:3], off
	s_waitcnt vmcnt(10)
	s_barrier
	v_and_b32_e32 v171, 15, v6
	v_lshlrev_b32_e32 v2, 4, v172
	v_lshlrev_b32_e32 v3, 2, v6
	s_and_b32 s1, s1, 3
	s_lshl_b32 s88, s4, 6
	v_lshl_or_b32 v2, v171, 6, v2
	s_lshl_b32 s4, s4, 13
	v_and_b32_e32 v3, 32, v3
	v_bitop3_b32 v4, v2, s4, v3 bitop3:0xde
	s_lshl_b32 s4, s1, 12
	s_cmpk_lt_u32 s0, 0x100
	s_waitcnt vmcnt(6)
	s_cselect_b64 s[58:59], -1, 0
	s_lshl_b32 s91, s1, 4
	v_readlane_b32 s0, v254, 16
	v_bitop3_b32 v173, v2, s4, v3 bitop3:0xde
	s_add_i32 s93, s2, s0
	s_add_i32 s95, 0, 0x10000
	s_add_i32 s96, 0, 0x14000
	s_mov_b32 s89, 0x18000
	s_mov_b32 s90, 0x8000
	s_ashr_i32 s92, s88, 31
	s_lshl_b32 s94, s93, 3
	v_add_u32_e32 v174, s95, v173
	v_add_u32_e32 v175, 0, v4
	v_add_u32_e32 v176, s96, v173
	s_mov_b64 s[60:61], 0x100
	s_mov_b64 s[62:63], 0x180
	s_mov_b32 s97, 0xbfb8aa3b
	s_mov_b32 s84, 0xb2a5705f
	s_mov_b32 s24, 0x42ce8ed0
	s_mov_b32 s25, 0xc2b17218
	s_mov_b32 s8, 0x7f800000
	s_mov_b32 s9, 0x3f2aaaab
	v_mov_b32_e32 v177, 0x3ecc95a3
	s_mov_b32 s85, 0x3f317218
	s_mov_b32 s86, 0x33800000
	s_mov_b32 s6, 0xbca3d70a
	s_mov_b32 s7, 0x3e2aaaab
	s_mov_b32 s4, 0x40000
	s_mov_b32 s5, 0x48000
	s_mov_b32 s28, 0x50000
	s_mov_b32 s29, 0x58000
	v_mov_b32_e32 v178, 0x7f800000
	v_mov_b32_e32 v146, 0x3f317218
	s_barrier
	v_readlane_b32 s1, v254, 17
	s_branch .LBB0_1233

.LBB0_1625:
	s_add_u32 s27, s10, 0x6e00000
	s_addc_u32 s28, s11, 0
	s_add_u32 s29, s10, 0x8e00000
	s_addc_u32 s33, s11, 0
	s_cmpk_lt_u32 s2, 0x100
	s_cselect_b32 s34, s33, 0
	s_cselect_b32 s35, s29, 0
	s_cmp_eq_u32 s31, 1
	s_cselect_b32 s37, s27, 0
	s_cselect_b32 s36, s28, 0
	s_add_u32 s35, s37, s35
	s_addc_u32 s34, s36, s34
	s_cmp_eq_u32 s31, 2
	s_cselect_b32 s36, s8, 0
	s_cselect_b32 s31, s9, 0
	s_add_u32 s35, s35, s36
	s_addc_u32 s31, s34, s31
	s_or_b32 s23, s23, s30
	s_lshl_b32 s23, s23, 1
	s_add_u32 s52, s35, s23
	s_addc_u32 s53, s31, 0
	s_add_u32 s64, s10, 0x2103000
	s_addc_u32 s65, s11, 0
	s_ashr_i32 s23, s22, 31
	s_lshl_b64 s[22:23], s[22:23], 2
	s_add_u32 s22, s64, s22
	s_addc_u32 s23, s65, s23
	s_lshl_b32 s30, s30, 2
	s_add_u32 s54, s22, s30
	s_addc_u32 s55, s23, 0
	s_mov_b64 s[22:23], 0x80
	v_lshl_add_u64 v[10:11], v[2:3], 0, s[22:23]
	s_add_i32 m0, s6, 0x18000
	s_mov_b64 s[34:35], 0x20080
	global_load_lds_dwordx4 v[10:11], off
	v_lshl_add_u64 v[10:11], v[2:3], 0, s[34:35]
	s_add_i32 m0, s6, 0x1a000
	s_add_i32 s66, s6, 0x8000
	global_load_lds_dwordx4 v[10:11], off
	v_lshl_add_u64 v[10:11], v[4:5], 0, s[22:23]
	s_mov_b32 m0, s66
	s_add_i32 s67, s6, 0xa000
	global_load_lds_dwordx4 v[10:11], off
	v_lshl_add_u64 v[4:5], v[4:5], 0, s[34:35]
	s_mov_b32 m0, s67
	s_mov_b64 s[36:37], 0x40080
	global_load_lds_dwordx4 v[4:5], off
	v_lshl_add_u64 v[4:5], v[2:3], 0, s[36:37]
	s_add_i32 m0, s6, 0x1c000
	s_mov_b64 s[38:39], 0x60080
	global_load_lds_dwordx4 v[4:5], off
	v_lshl_add_u64 v[2:3], v[2:3], 0, s[38:39]
	s_add_i32 m0, s6, 0x1e000
	v_bfe_u32 v187, v6, 4, 2
	global_load_lds_dwordx4 v[2:3], off
	s_waitcnt vmcnt(10)
	s_barrier
	s_lshl_b32 s1, s1, 5
	v_and_b32_e32 v186, 15, v6
	v_lshlrev_b32_e32 v2, 4, v187
	v_lshlrev_b32_e32 v3, 2, v6
	s_and_b32 s69, s1, 0x60
	s_lshl_b32 s68, s18, 6
	v_lshl_or_b32 v2, v186, 6, v2
	s_lshl_b32 s18, s18, 13
	v_and_b32_e32 v3, 32, v3
	s_lshl_b32 s1, s69, 7
	v_bitop3_b32 v4, v2, s18, v3 bitop3:0xde
	v_bitop3_b32 v188, v2, s1, v3 bitop3:0xde
	v_lshlrev_b32_e32 v2, 14, v8
	v_and_b32_e32 v2, 0xffff8000, v2
	s_waitcnt vmcnt(6)
	s_cmpk_lt_u32 s0, 0x100
	v_lshl_add_u32 v2, v7, 11, v2
	v_and_b32_e32 v3, 1, v8
	s_cselect_b64 s[40:41], -1, 0
	v_lshl_or_b32 v2, v3, 6, v2
	s_add_i32 s72, 0, 0x10000
	s_add_i32 s73, 0, 0x14000
	s_mov_b32 s70, 0x18000
	s_mov_b32 s71, 0x8000
	v_lshl_add_u32 v166, v9, 1, v2
	v_mov_b32_e32 v167, v163
	v_add_u32_e32 v189, s72, v188
	v_add_u32_e32 v190, 0, v4
	v_add_u32_e32 v191, s73, v188
	s_lshl_b32 s18, s69, 1
	s_mov_b32 s74, 0x40000
	s_mov_b32 s75, 0x48000
	s_mov_b32 s76, 0x50000
	s_mov_b32 s77, 0x58000
	s_mov_b32 s78, s19
	s_barrier
	s_branch .LBB0_1628

.LBB0_1696:
	s_add_u32 s26, s14, 0x1200000
	s_addc_u32 s27, s15, 0
	s_add_u32 s28, s14, 0x8e00000
	s_addc_u32 s29, s15, 0
	s_add_u32 s33, s14, 0x6e00000
	s_addc_u32 s64, s15, 0
	s_add_u32 s34, s12, 0x2000000
	s_addc_u32 s35, s13, 0
	s_add_u32 s36, s14, 0xce00000
	s_mov_b64 s[38:39], 0x80
	s_addc_u32 s37, s15, 0
	v_lshl_add_u64 v[10:11], v[2:3], 0, s[38:39]
	s_add_i32 m0, s6, 0x18000
	s_mov_b64 s[40:41], 0x20080
	global_load_lds_dwordx4 v[10:11], off
	v_lshl_add_u64 v[10:11], v[2:3], 0, s[40:41]
	s_add_i32 m0, s6, 0x1a000
	s_add_i32 s65, s6, 0x8000
	global_load_lds_dwordx4 v[10:11], off
	v_lshl_add_u64 v[10:11], v[4:5], 0, s[38:39]
	s_mov_b32 m0, s65
	s_add_i32 s66, s6, 0xa000
	global_load_lds_dwordx4 v[10:11], off
	v_lshl_add_u64 v[4:5], v[4:5], 0, s[40:41]
	s_mov_b32 m0, s66
	s_mov_b64 s[42:43], 0x40080
	global_load_lds_dwordx4 v[4:5], off
	v_lshl_add_u64 v[4:5], v[2:3], 0, s[42:43]
	s_add_i32 m0, s6, 0x1c000
	s_mov_b64 s[44:45], 0x60080
	global_load_lds_dwordx4 v[4:5], off
	v_lshl_add_u64 v[2:3], v[2:3], 0, s[44:45]
	s_add_i32 m0, s6, 0x1e000
	v_bfe_u32 v211, v6, 4, 2
	global_load_lds_dwordx4 v[2:3], off
	s_waitcnt vmcnt(10)
	s_barrier
	s_lshl_b32 s1, s1, 5
	v_and_b32_e32 v210, 15, v6
	v_lshlrev_b32_e32 v2, 4, v211
	v_lshlrev_b32_e32 v3, 2, v6
	s_and_b32 s68, s1, 0x60
	s_lshl_b32 s67, s8, 6
	v_lshl_or_b32 v2, v210, 6, v2
	s_lshl_b32 s8, s8, 13
	v_and_b32_e32 v3, 32, v3
	s_lshl_b32 s1, s68, 7
	v_bitop3_b32 v4, v2, s8, v3 bitop3:0xde
	v_bitop3_b32 v212, v2, s1, v3 bitop3:0xde
	v_lshlrev_b32_e32 v2, 14, v7
	s_cmpk_lt_u32 s0, 0x100
	v_and_b32_e32 v2, 0xffff8000, v2
	s_waitcnt vmcnt(6)
	s_cselect_b64 s[46:47], -1, 0
	s_add_u32 s71, s14, 0x2106000
	v_lshl_add_u32 v2, v8, 11, v2
	v_and_b32_e32 v3, 1, v7
	s_addc_u32 s72, s15, 0
	v_lshl_or_b32 v2, v3, 6, v2
	s_add_i32 s73, 0, 0x10000
	s_add_i32 s74, 0, 0x14000
	s_mov_b32 s69, 0x18000
	s_mov_b32 s70, 0x8000
	v_lshl_add_u32 v198, v9, 1, v2
	v_mov_b32_e32 v199, v197
	v_add_u32_e32 v213, s73, v212
	v_add_u32_e32 v214, 0, v4
	v_add_u32_e32 v215, s74, v212
	s_mov_b32 s75, 0x40000
	s_mov_b32 s76, 0x48000
	s_mov_b32 s77, 0x50000
	s_mov_b32 s78, 0x58000
	s_mov_b32 s79, 0x42a00000
	s_mov_b32 s85, 0
	s_mov_b32 s81, 0
	s_barrier
	s_branch .LBB0_1699

.LBB0_1841:
	v_bfe_u32 v244, v6, 4, 2
	v_and_b32_e32 v245, 15, v6
	v_lshlrev_b32_e32 v10, 4, v244
	v_lshlrev_b32_e32 v6, 2, v6
	s_and_b32 s4, s0, 3
	v_lshl_or_b32 v10, v245, 6, v10
	s_lshl_b32 s0, s5, 13
	v_and_b32_e32 v6, 32, v6
	v_bitop3_b32 v12, v10, s0, v6 bitop3:0xde
	s_lshl_b32 s0, s4, 12
	v_bitop3_b32 v6, v10, s0, v6 bitop3:0xde
	s_mov_b64 s[0:1], 0x80
	v_lshl_add_u64 v[10:11], v[2:3], 0, s[0:1]
	s_add_i32 m0, s15, 0x18000
	s_mov_b64 s[28:29], 0x20080
	global_load_lds_dwordx4 v[10:11], off
	v_lshl_add_u64 v[10:11], v[2:3], 0, s[28:29]
	s_add_i32 m0, s15, 0x1a000
	s_add_i32 s43, s15, 0x8000
	global_load_lds_dwordx4 v[10:11], off
	v_lshl_add_u64 v[10:11], v[4:5], 0, s[0:1]
	s_mov_b32 m0, s43
	s_add_i32 s44, s15, 0xa000
	global_load_lds_dwordx4 v[10:11], off
	v_lshl_add_u64 v[4:5], v[4:5], 0, s[28:29]
	s_mov_b32 m0, s44
	s_mov_b64 s[30:31], 0x40080
	global_load_lds_dwordx4 v[4:5], off
	v_lshl_add_u64 v[4:5], v[2:3], 0, s[30:31]
	s_add_i32 m0, s15, 0x1c000
	s_mov_b64 s[34:35], 0x60080
	global_load_lds_dwordx4 v[4:5], off
	v_lshl_add_u64 v[2:3], v[2:3], 0, s[34:35]
	s_add_i32 m0, s15, 0x1e000
	s_add_i32 s48, 0, 0x10000
	global_load_lds_dwordx4 v[2:3], off
	s_waitcnt vmcnt(10)
	s_barrier
	v_lshlrev_b32_e32 v2, 14, v7
	v_and_b32_e32 v2, 0xffff8000, v2
	v_lshl_add_u32 v2, v8, 11, v2
	v_and_b32_e32 v3, 1, v7
	s_waitcnt vmcnt(6)
	v_lshl_or_b32 v2, v3, 6, v2
	s_add_i32 s50, 0, 0x14000
	s_add_i32 s52, 0, 0x18000
	s_add_i32 s54, 0, 0x1c000
	v_lshl_add_u32 v2, v9, 1, v2
	v_mov_b32_e32 v3, v133
	v_add_u32_e32 v136, s48, v6
	v_add_u32_e32 v138, s50, v6
	s_add_i32 s48, s48, s38
	s_add_i32 s50, s50, s38
	v_add_u32_e32 v139, s52, v6
	v_add_u32_e32 v140, s54, v6
	s_add_i32 s52, s52, s38
	s_add_i32 s54, s54, s38
	s_lshl_b32 s25, s5, 6
	v_lshl_add_u64 v[134:135], s[20:21], 0, v[2:3]
	s_mov_b32 s45, -2
	s_mov_b64 s[36:37], 0
	v_add_u32_e32 v137, 0, v12
	s_add_i32 s46, s15, 0xc000
	s_add_i32 s47, s15, 0xe000
	s_add_i32 s49, s48, 0x2000
	s_add_i32 s51, s50, 0x2000
	s_add_i32 s53, s52, 0x2000
	s_add_i32 s55, s54, 0x2000
	v_mov_b32_e32 v2, v133
	v_mov_b32_e32 v4, v133
	v_mov_b32_e32 v5, v133
	v_mov_b32_e32 v6, v133
	v_mov_b32_e32 v7, v133
	v_mov_b32_e32 v8, v133
	v_mov_b32_e32 v9, v133
	v_mov_b32_e32 v18, v133
	v_mov_b32_e32 v19, v133
	v_mov_b32_e32 v20, v133
	v_mov_b32_e32 v21, v133
	v_mov_b32_e32 v22, v133
	v_mov_b32_e32 v23, v133
	v_mov_b32_e32 v24, v133
	v_mov_b32_e32 v25, v133
	v_mov_b32_e32 v34, v133
	v_mov_b32_e32 v35, v133
	v_mov_b32_e32 v36, v133
	v_mov_b32_e32 v37, v133
	v_mov_b32_e32 v38, v133
	v_mov_b32_e32 v39, v133
	v_mov_b32_e32 v40, v133
	v_mov_b32_e32 v41, v133
	v_mov_b32_e32 v50, v133
	v_mov_b32_e32 v51, v133
	v_mov_b32_e32 v52, v133
	v_mov_b32_e32 v53, v133
	v_mov_b32_e32 v54, v133
	v_mov_b32_e32 v55, v133
	v_mov_b32_e32 v56, v133
	v_mov_b32_e32 v57, v133
	v_mov_b32_e32 v10, v133
	v_mov_b32_e32 v11, v133
	v_mov_b32_e32 v12, v133
	v_mov_b32_e32 v13, v133
	v_mov_b32_e32 v14, v133
	v_mov_b32_e32 v15, v133
	v_mov_b32_e32 v16, v133
	v_mov_b32_e32 v17, v133
	v_mov_b32_e32 v26, v133
	v_mov_b32_e32 v27, v133
	v_mov_b32_e32 v28, v133
	v_mov_b32_e32 v29, v133
	v_mov_b32_e32 v30, v133
	v_mov_b32_e32 v31, v133
	v_mov_b32_e32 v32, v133
	v_mov_b32_e32 v33, v133
	v_mov_b32_e32 v42, v133
	v_mov_b32_e32 v43, v133
	v_mov_b32_e32 v44, v133
	v_mov_b32_e32 v45, v133
	v_mov_b32_e32 v46, v133
	v_mov_b32_e32 v47, v133
	v_mov_b32_e32 v48, v133
	v_mov_b32_e32 v49, v133
	v_mov_b32_e32 v58, v133
	v_mov_b32_e32 v59, v133
	v_mov_b32_e32 v60, v133
	v_mov_b32_e32 v61, v133
	v_mov_b32_e32 v62, v133
	v_mov_b32_e32 v63, v133
	v_mov_b32_e32 v64, v133
	v_mov_b32_e32 v65, v133
	v_mov_b32_e32 v66, v133
	v_mov_b32_e32 v67, v133
	v_mov_b32_e32 v68, v133
	v_mov_b32_e32 v69, v133
	v_mov_b32_e32 v70, v133
	v_mov_b32_e32 v71, v133
	v_mov_b32_e32 v72, v133
	v_mov_b32_e32 v73, v133
	v_mov_b32_e32 v82, v133
	v_mov_b32_e32 v83, v133
	v_mov_b32_e32 v84, v133
	v_mov_b32_e32 v85, v133
	v_mov_b32_e32 v86, v133
	v_mov_b32_e32 v87, v133
	v_mov_b32_e32 v88, v133
	v_mov_b32_e32 v89, v133
	v_mov_b32_e32 v98, v133
	v_mov_b32_e32 v99, v133
	v_mov_b32_e32 v100, v133
	v_mov_b32_e32 v101, v133
	v_mov_b32_e32 v102, v133
	v_mov_b32_e32 v103, v133
	v_mov_b32_e32 v104, v133
	v_mov_b32_e32 v105, v133
	v_mov_b32_e32 v114, v133
	v_mov_b32_e32 v115, v133
	v_mov_b32_e32 v116, v133
	v_mov_b32_e32 v117, v133
	v_mov_b32_e32 v118, v133
	v_mov_b32_e32 v119, v133
	v_mov_b32_e32 v120, v133
	v_mov_b32_e32 v121, v133
	v_mov_b32_e32 v74, v133
	v_mov_b32_e32 v75, v133
	v_mov_b32_e32 v76, v133
	v_mov_b32_e32 v77, v133
	v_mov_b32_e32 v78, v133
	v_mov_b32_e32 v79, v133
	v_mov_b32_e32 v80, v133
	v_mov_b32_e32 v81, v133
	v_mov_b32_e32 v90, v133
	v_mov_b32_e32 v91, v133
	v_mov_b32_e32 v92, v133
	v_mov_b32_e32 v93, v133
	v_mov_b32_e32 v94, v133
	v_mov_b32_e32 v95, v133
	v_mov_b32_e32 v96, v133
	v_mov_b32_e32 v97, v133
	v_mov_b32_e32 v106, v133
	v_mov_b32_e32 v107, v133
	v_mov_b32_e32 v108, v133
	v_mov_b32_e32 v109, v133
	v_mov_b32_e32 v110, v133
	v_mov_b32_e32 v111, v133
	v_mov_b32_e32 v112, v133
	v_mov_b32_e32 v113, v133
	v_mov_b32_e32 v122, v133
	v_mov_b32_e32 v123, v133
	v_mov_b32_e32 v124, v133
	v_mov_b32_e32 v125, v133
	v_mov_b32_e32 v126, v133
	v_mov_b32_e32 v127, v133
	v_mov_b32_e32 v128, v133
	v_mov_b32_e32 v129, v133
	s_barrier
